# saddr-form LDS-DMA addresses also in the P1 bf16, P1 int8 and P4 K-loops (all copies)
# speedup vs baseline: 1.0153x; 1.0005x over previous
.LBB0_236:
	s_add_i32 s12, s75, 2
	s_add_u32 s30, s28, 0xfff00080
	s_addc_u32 s31, s29, -1
	s_cmp_eq_u32 s72, s75
	s_cselect_b32 s35, s68, s31
	s_cselect_b32 s34, s69, s30
	s_cselect_b32 s31, s70, s74
	s_cselect_b32 s30, s71, s73
	s_cmpk_lt_i32 s3, 0x56
	s_cselect_b32 s36, s58, 0x2b00
	s_mov_b32 s37, 0xac00
	s_cselect_b32 s75, s37, 0x4000
	s_sub_i32 s36, s36, s33
	v_min3_i32 v5, s36, v174, 2
	v_sub_u32_e32 v174, v174, v5
	v_readfirstlane_b32 s78, v5
	s_max_i32 s36, s78, 0
	s_add_i32 s36, s33, s36
	s_add_i32 s76, s36, -1
	s_min_i32 s36, s33, s76
	s_mul_hi_i32 s37, s75, s36
	s_mul_i32 s36, s75, s36
	s_add_u32 s36, s38, s36
	s_addc_u32 s37, s39, s37
	s_mul_hi_i32 s77, s75, s76
	s_mul_i32 s75, s75, s76
	s_add_u32 s76, s38, s75
	global_load_dwordx4 v[152:155], v173, s[36:37] nt
	s_addc_u32 s77, s39, s77
	global_load_dwordx4 v[164:167], v173, s[76:77] nt
	s_add_i32 s33, s78, s33
	v_add_u32_e32 v5, s59, v160
	ds_read_b128 v[168:171], v5
	ds_read_b128 v[176:179], v5 offset:1024
	ds_read_b128 v[180:183], v5 offset:2048
	ds_read_b128 v[184:187], v5 offset:3072
	v_add_u32_e32 v5, s60, v160
	ds_read_b128 v[188:191], v5
	ds_read_b128 v[192:195], v5 offset:1024
	ds_read_b128 v[196:199], v5 offset:2048
	ds_read_b128 v[200:203], v5 offset:3072
	s_add_i32 m0, s49, 0xc000
	ds_read_b128 v[204:207], v163
	ds_read_b128 v[208:211], v163 offset:1024
	ds_read_b128 v[212:215], v163 offset:2048
	ds_read_b128 v[216:219], v163 offset:3072
	ds_read_b128 v[220:223], v163 offset:4096
	ds_read_b128 v[224:227], v163 offset:5120
	ds_read_b128 v[228:231], v163 offset:6144
	ds_read_b128 v[236:239], v163 offset:7168
	global_load_lds_dwordx4 v146, s[28:29]
	s_add_i32 m0, s49, 0xe000
	s_nop 0
	global_load_lds_dwordx4 v148, s[28:29]
	s_waitcnt vmcnt(10)
	s_waitcnt lgkmcnt(0)
	s_barrier
	s_setprio 1
	s_waitcnt lgkmcnt(0)
	v_mfma_f32_16x16x32_bf16 v[132:135], v[168:171], v[204:207], v[132:135]
	v_mfma_f32_16x16x32_bf16 v[128:131], v[180:183], v[204:207], v[128:131]
	v_mfma_f32_16x16x32_bf16 v[116:119], v[168:171], v[212:215], v[116:119]
	v_mfma_f32_16x16x32_bf16 v[112:115], v[180:183], v[212:215], v[112:115]
	v_mfma_f32_16x16x32_bf16 v[100:103], v[168:171], v[220:223], v[100:103]
	v_mfma_f32_16x16x32_bf16 v[96:99], v[180:183], v[220:223], v[96:99]
	v_mfma_f32_16x16x32_bf16 v[84:87], v[168:171], v[228:231], v[84:87]
	v_mfma_f32_16x16x32_bf16 v[80:83], v[180:183], v[228:231], v[80:83]
	v_mfma_f32_16x16x32_bf16 v[132:135], v[176:179], v[208:211], v[132:135]
	v_mfma_f32_16x16x32_bf16 v[128:131], v[184:187], v[208:211], v[128:131]
	v_mfma_f32_16x16x32_bf16 v[116:119], v[176:179], v[216:219], v[116:119]
	v_mfma_f32_16x16x32_bf16 v[112:115], v[184:187], v[216:219], v[112:115]
	v_mfma_f32_16x16x32_bf16 v[100:103], v[176:179], v[224:227], v[100:103]
	v_mfma_f32_16x16x32_bf16 v[96:99], v[184:187], v[224:227], v[96:99]
	v_mfma_f32_16x16x32_bf16 v[84:87], v[176:179], v[236:239], v[84:87]
	v_mfma_f32_16x16x32_bf16 v[80:83], v[184:187], v[236:239], v[80:83]
	s_setprio 0
	s_setprio 1
	v_mfma_f32_16x16x32_bf16 v[124:127], v[188:191], v[204:207], v[124:127]
	v_mfma_f32_16x16x32_bf16 v[120:123], v[196:199], v[204:207], v[120:123]
	v_mfma_f32_16x16x32_bf16 v[108:111], v[188:191], v[212:215], v[108:111]
	v_mfma_f32_16x16x32_bf16 v[104:107], v[196:199], v[212:215], v[104:107]
	v_mfma_f32_16x16x32_bf16 v[92:95], v[188:191], v[220:223], v[92:95]
	v_mfma_f32_16x16x32_bf16 v[88:91], v[196:199], v[220:223], v[88:91]
	v_mfma_f32_16x16x32_bf16 v[76:79], v[188:191], v[228:231], v[76:79]
	v_mfma_f32_16x16x32_bf16 v[72:75], v[196:199], v[228:231], v[72:75]
	v_mfma_f32_16x16x32_bf16 v[124:127], v[192:195], v[208:211], v[124:127]
	v_mfma_f32_16x16x32_bf16 v[120:123], v[200:203], v[208:211], v[120:123]
	v_mfma_f32_16x16x32_bf16 v[108:111], v[192:195], v[216:219], v[108:111]
	v_mfma_f32_16x16x32_bf16 v[104:107], v[200:203], v[216:219], v[104:107]
	v_mfma_f32_16x16x32_bf16 v[92:95], v[192:195], v[224:227], v[92:95]
	v_mfma_f32_16x16x32_bf16 v[88:91], v[200:203], v[224:227], v[88:91]
	v_mfma_f32_16x16x32_bf16 v[76:79], v[192:195], v[236:239], v[76:79]
	v_mfma_f32_16x16x32_bf16 v[72:75], v[200:203], v[236:239], v[72:75]
	s_setprio 0
	s_barrier
	s_add_i32 s36, s59, s48
	s_mov_b32 m0, s36
	ds_read_b128 v[204:207], v163 offset:16384
	ds_read_b128 v[208:211], v163 offset:17408
	ds_read_b128 v[212:215], v163 offset:18432
	ds_read_b128 v[216:219], v163 offset:19456
	ds_read_b128 v[220:223], v163 offset:20480
	ds_read_b128 v[224:227], v163 offset:21504
	ds_read_b128 v[228:231], v163 offset:22528
	ds_read_b128 v[236:239], v163 offset:23552
	global_load_lds_dwordx4 v138, s[30:31]
	s_add_i32 m0, s36, 0x2000
	s_add_u32 s36, s30, 0x100000
	s_addc_u32 s37, s31, 0
	s_add_i32 s75, s60, s48
	global_load_lds_dwordx4 v142, s[30:31]
	s_mov_b32 m0, s75
	s_nop 0
	global_load_lds_dwordx4 v138, s[36:37]
	s_add_i32 m0, s75, 0x2000
	s_nop 0
	global_load_lds_dwordx4 v142, s[36:37]
	s_mov_b32 m0, s49
	s_nop 0
	global_load_lds_dwordx4 v136, s[34:35]
	s_mov_b32 m0, s50
	s_nop 0
	global_load_lds_dwordx4 v140, s[34:35]
	s_waitcnt vmcnt(10)
	s_waitcnt lgkmcnt(0)
	s_barrier
	s_setprio 1
	s_waitcnt lgkmcnt(0)
	v_mfma_f32_16x16x32_bf16 v[68:71], v[168:171], v[204:207], v[68:71]
	v_mfma_f32_16x16x32_bf16 v[64:67], v[180:183], v[204:207], v[64:67]
	v_mfma_f32_16x16x32_bf16 v[52:55], v[168:171], v[212:215], v[52:55]
	v_mfma_f32_16x16x32_bf16 v[48:51], v[180:183], v[212:215], v[48:51]
	v_mfma_f32_16x16x32_bf16 v[36:39], v[168:171], v[220:223], v[36:39]
	v_mfma_f32_16x16x32_bf16 v[32:35], v[180:183], v[220:223], v[32:35]
	v_mfma_f32_16x16x32_bf16 v[20:23], v[168:171], v[228:231], v[20:23]
	v_mfma_f32_16x16x32_bf16 v[16:19], v[180:183], v[228:231], v[16:19]
	v_mfma_f32_16x16x32_bf16 v[68:71], v[176:179], v[208:211], v[68:71]
	v_mfma_f32_16x16x32_bf16 v[64:67], v[184:187], v[208:211], v[64:67]
	v_mfma_f32_16x16x32_bf16 v[52:55], v[176:179], v[216:219], v[52:55]
	v_mfma_f32_16x16x32_bf16 v[48:51], v[184:187], v[216:219], v[48:51]
	v_mfma_f32_16x16x32_bf16 v[36:39], v[176:179], v[224:227], v[36:39]
	v_mfma_f32_16x16x32_bf16 v[32:35], v[184:187], v[224:227], v[32:35]
	v_mfma_f32_16x16x32_bf16 v[20:23], v[176:179], v[236:239], v[20:23]
	v_mfma_f32_16x16x32_bf16 v[16:19], v[184:187], v[236:239], v[16:19]
	s_setprio 0
	s_setprio 1
	v_mfma_f32_16x16x32_bf16 v[60:63], v[188:191], v[204:207], v[60:63]
	v_mfma_f32_16x16x32_bf16 v[56:59], v[196:199], v[204:207], v[56:59]
	v_mfma_f32_16x16x32_bf16 v[44:47], v[188:191], v[212:215], v[44:47]
	v_mfma_f32_16x16x32_bf16 v[40:43], v[196:199], v[212:215], v[40:43]
	v_mfma_f32_16x16x32_bf16 v[28:31], v[188:191], v[220:223], v[28:31]
	v_mfma_f32_16x16x32_bf16 v[24:27], v[196:199], v[220:223], v[24:27]
	v_mfma_f32_16x16x32_bf16 v[12:15], v[188:191], v[228:231], v[12:15]
	v_mfma_f32_16x16x32_bf16 v[6:9], v[196:199], v[228:231], v[8:11]
	v_mfma_f32_16x16x32_bf16 v[60:63], v[192:195], v[208:211], v[60:63]
	v_mfma_f32_16x16x32_bf16 v[56:59], v[200:203], v[208:211], v[56:59]
	v_mfma_f32_16x16x32_bf16 v[44:47], v[192:195], v[216:219], v[44:47]
	v_mfma_f32_16x16x32_bf16 v[40:43], v[200:203], v[216:219], v[40:43]
	v_mfma_f32_16x16x32_bf16 v[28:31], v[192:195], v[224:227], v[28:31]
	v_mfma_f32_16x16x32_bf16 v[24:27], v[200:203], v[224:227], v[24:27]
	v_mfma_f32_16x16x32_bf16 v[12:15], v[192:195], v[236:239], v[12:15]
	v_mfma_f32_16x16x32_bf16 v[6:9], v[200:203], v[236:239], v[6:9]
	s_setprio 0
	s_barrier
	s_add_i32 s36, 0, 0x18000
	v_add_u32_e32 v5, s36, v160
	s_add_i32 s37, 0, 0x1c000
	ds_read_b128 v[168:171], v5
	ds_read_b128 v[176:179], v5 offset:1024
	ds_read_b128 v[180:183], v5 offset:2048
	ds_read_b128 v[184:187], v5 offset:3072
	v_add_u32_e32 v5, s37, v160
	ds_read_b128 v[188:191], v5
	ds_read_b128 v[192:195], v5 offset:1024
	ds_read_b128 v[196:199], v5 offset:2048
	ds_read_b128 v[200:203], v5 offset:3072
	s_add_u32 s34, s34, 0x100000
	s_addc_u32 s35, s35, 0
	s_mov_b32 m0, s51
	ds_read_b128 v[204:207], v163 offset:32768
	ds_read_b128 v[208:211], v163 offset:33792
	ds_read_b128 v[212:215], v163 offset:34816
	ds_read_b128 v[216:219], v163 offset:35840
	ds_read_b128 v[220:223], v163 offset:36864
	ds_read_b128 v[224:227], v163 offset:37888
	ds_read_b128 v[228:231], v163 offset:38912
	ds_read_b128 v[236:239], v163 offset:39936
	global_load_lds_dwordx4 v136, s[34:35]
	s_mov_b32 m0, s52
	s_nop 0
	global_load_lds_dwordx4 v140, s[34:35]
	s_waitcnt vmcnt(8)
	s_waitcnt lgkmcnt(0)
	s_barrier
	s_setprio 1
	s_waitcnt lgkmcnt(0)
	v_mfma_f32_16x16x32_bf16 v[132:135], v[168:171], v[204:207], v[132:135]
	v_mfma_f32_16x16x32_bf16 v[128:131], v[180:183], v[204:207], v[128:131]
	v_mfma_f32_16x16x32_bf16 v[116:119], v[168:171], v[212:215], v[116:119]
	v_mfma_f32_16x16x32_bf16 v[112:115], v[180:183], v[212:215], v[112:115]
	v_mfma_f32_16x16x32_bf16 v[100:103], v[168:171], v[220:223], v[100:103]
	v_max3_f32 v0, v0, |v152|, |v164|
	v_mfma_f32_16x16x32_bf16 v[96:99], v[180:183], v[220:223], v[96:99]
	v_max3_f32 v1, v1, |v153|, |v165|
	v_mfma_f32_16x16x32_bf16 v[84:87], v[168:171], v[228:231], v[84:87]
	v_max3_f32 v2, v2, |v154|, |v166|
	v_mfma_f32_16x16x32_bf16 v[80:83], v[180:183], v[228:231], v[80:83]
	v_max3_f32 v3, v3, |v155|, |v167|
	v_mfma_f32_16x16x32_bf16 v[132:135], v[176:179], v[208:211], v[132:135]
	v_mfma_f32_16x16x32_bf16 v[128:131], v[184:187], v[208:211], v[128:131]
	v_mfma_f32_16x16x32_bf16 v[116:119], v[176:179], v[216:219], v[116:119]
	v_mfma_f32_16x16x32_bf16 v[112:115], v[184:187], v[216:219], v[112:115]
	v_mfma_f32_16x16x32_bf16 v[100:103], v[176:179], v[224:227], v[100:103]
	v_mfma_f32_16x16x32_bf16 v[96:99], v[184:187], v[224:227], v[96:99]
	v_mfma_f32_16x16x32_bf16 v[84:87], v[176:179], v[236:239], v[84:87]
	v_mfma_f32_16x16x32_bf16 v[80:83], v[184:187], v[236:239], v[80:83]
	s_setprio 0
	s_setprio 1
	v_mfma_f32_16x16x32_bf16 v[124:127], v[188:191], v[204:207], v[124:127]
	v_mfma_f32_16x16x32_bf16 v[120:123], v[196:199], v[204:207], v[120:123]
	v_mfma_f32_16x16x32_bf16 v[108:111], v[188:191], v[212:215], v[108:111]
	v_mfma_f32_16x16x32_bf16 v[104:107], v[196:199], v[212:215], v[104:107]
	v_mfma_f32_16x16x32_bf16 v[92:95], v[188:191], v[220:223], v[92:95]
	v_mfma_f32_16x16x32_bf16 v[88:91], v[196:199], v[220:223], v[88:91]
	v_mfma_f32_16x16x32_bf16 v[76:79], v[188:191], v[228:231], v[76:79]
	v_mfma_f32_16x16x32_bf16 v[72:75], v[196:199], v[228:231], v[72:75]
	v_mfma_f32_16x16x32_bf16 v[124:127], v[192:195], v[208:211], v[124:127]
	v_mfma_f32_16x16x32_bf16 v[120:123], v[200:203], v[208:211], v[120:123]
	v_mfma_f32_16x16x32_bf16 v[108:111], v[192:195], v[216:219], v[108:111]
	v_mfma_f32_16x16x32_bf16 v[104:107], v[200:203], v[216:219], v[104:107]
	v_mfma_f32_16x16x32_bf16 v[92:95], v[192:195], v[224:227], v[92:95]
	v_mfma_f32_16x16x32_bf16 v[88:91], v[200:203], v[224:227], v[88:91]
	v_mfma_f32_16x16x32_bf16 v[76:79], v[192:195], v[236:239], v[76:79]
	v_mfma_f32_16x16x32_bf16 v[72:75], v[200:203], v[236:239], v[72:75]
	s_setprio 0
	s_barrier
	s_add_u32 s98, s30, s10
	s_addc_u32 s99, s31, s11
	s_add_u32 s100, s34, s10
	s_addc_u32 s101, s35, s11
	s_sub_u32 s100, s100, 0x100000
	s_subb_u32 s101, s101, 0
	s_add_i32 s34, s36, s48
	s_mov_b32 m0, s34
	ds_read_b128 v[152:155], v163 offset:49152
	ds_read_b128 v[164:167], v163 offset:50176
	ds_read_b128 v[204:207], v163 offset:51200
	ds_read_b128 v[208:211], v163 offset:52224
	ds_read_b128 v[212:215], v163 offset:53248
	ds_read_b128 v[216:219], v163 offset:54272
	ds_read_b128 v[220:223], v163 offset:55296
	ds_read_b128 v[224:227], v163 offset:56320
	global_load_lds_dwordx4 v138, s[98:99]
	s_add_i32 m0, s34, 0x2000
	s_add_u32 s30, s30, 0x100080
	s_addc_u32 s31, s31, 0
	s_add_i32 s34, s37, s48
	global_load_lds_dwordx4 v142, s[98:99]
	s_mov_b32 m0, s34
	s_nop 0
	global_load_lds_dwordx4 v138, s[30:31]
	s_add_i32 m0, s34, 0x2000
	s_nop 0
	global_load_lds_dwordx4 v142, s[30:31]
	s_mov_b32 m0, s56
	s_nop 0
	global_load_lds_dwordx4 v136, s[100:101]
	s_mov_b32 m0, s57
	s_nop 0
	global_load_lds_dwordx4 v140, s[100:101]
	s_waitcnt vmcnt(8)
	s_waitcnt lgkmcnt(0)
	s_barrier
	s_setprio 1
	s_waitcnt lgkmcnt(0)
	v_mfma_f32_16x16x32_bf16 v[68:71], v[168:171], v[152:155], v[68:71]
	v_mfma_f32_16x16x32_bf16 v[64:67], v[180:183], v[152:155], v[64:67]
	v_mfma_f32_16x16x32_bf16 v[52:55], v[168:171], v[204:207], v[52:55]
	v_mfma_f32_16x16x32_bf16 v[48:51], v[180:183], v[204:207], v[48:51]
	v_mfma_f32_16x16x32_bf16 v[36:39], v[168:171], v[212:215], v[36:39]
	v_mfma_f32_16x16x32_bf16 v[32:35], v[180:183], v[212:215], v[32:35]
	v_mfma_f32_16x16x32_bf16 v[20:23], v[168:171], v[220:223], v[20:23]
	v_mfma_f32_16x16x32_bf16 v[16:19], v[180:183], v[220:223], v[16:19]
	v_mfma_f32_16x16x32_bf16 v[68:71], v[176:179], v[164:167], v[68:71]
	v_mfma_f32_16x16x32_bf16 v[64:67], v[184:187], v[164:167], v[64:67]
	v_mfma_f32_16x16x32_bf16 v[52:55], v[176:179], v[208:211], v[52:55]
	v_mfma_f32_16x16x32_bf16 v[48:51], v[184:187], v[208:211], v[48:51]
	v_mfma_f32_16x16x32_bf16 v[36:39], v[176:179], v[216:219], v[36:39]
	v_mfma_f32_16x16x32_bf16 v[32:35], v[184:187], v[216:219], v[32:35]
	v_mfma_f32_16x16x32_bf16 v[20:23], v[176:179], v[224:227], v[20:23]
	v_mfma_f32_16x16x32_bf16 v[16:19], v[184:187], v[224:227], v[16:19]
	s_setprio 0
	s_setprio 1
	v_mfma_f32_16x16x32_bf16 v[60:63], v[188:191], v[152:155], v[60:63]
	v_mfma_f32_16x16x32_bf16 v[56:59], v[196:199], v[152:155], v[56:59]
	v_mfma_f32_16x16x32_bf16 v[44:47], v[188:191], v[204:207], v[44:47]
	v_mfma_f32_16x16x32_bf16 v[40:43], v[196:199], v[204:207], v[40:43]
	v_mfma_f32_16x16x32_bf16 v[28:31], v[188:191], v[212:215], v[28:31]
	v_mfma_f32_16x16x32_bf16 v[24:27], v[196:199], v[212:215], v[24:27]
	v_mfma_f32_16x16x32_bf16 v[10:13], v[188:191], v[220:223], v[12:15]
	v_mfma_f32_16x16x32_bf16 v[6:9], v[196:199], v[220:223], v[6:9]
	v_mfma_f32_16x16x32_bf16 v[60:63], v[192:195], v[164:167], v[60:63]
	v_mfma_f32_16x16x32_bf16 v[56:59], v[200:203], v[164:167], v[56:59]
	v_mfma_f32_16x16x32_bf16 v[44:47], v[192:195], v[208:211], v[44:47]
	v_mfma_f32_16x16x32_bf16 v[40:43], v[200:203], v[208:211], v[40:43]
	v_mfma_f32_16x16x32_bf16 v[28:31], v[192:195], v[216:219], v[28:31]
	v_mfma_f32_16x16x32_bf16 v[24:27], v[200:203], v[216:219], v[24:27]
	v_mfma_f32_16x16x32_bf16 v[12:15], v[192:195], v[224:227], v[10:13]
	v_mfma_f32_16x16x32_bf16 v[8:11], v[200:203], v[224:227], v[6:9]
	s_setprio 0
	s_barrier
	s_add_u32 s28, s28, 0x100
	s_addc_u32 s29, s29, 0
	s_add_u32 s73, s73, 0x100
	s_addc_u32 s74, s74, 0
	s_cmp_ge_i32 s12, s67
	s_cbranch_scc0 .LBB0_221
	s_and_b64 vcc, exec, s[14:15]
	s_cbranch_vccz .LBB0_239

.Lp1i_body:
	s_add_i32 s8, s74, 2
	s_add_u32 s34, s30, 0xfff80080
	s_addc_u32 s35, s31, -1
	s_cmp_eq_u32 s71, s74
	s_cselect_b32 s37, s67, s35
	s_cselect_b32 s36, s68, s34
	s_cselect_b32 s35, s69, s73
	s_cselect_b32 s34, s70, s72
	v_add_u32_e32 v5, s57, v177
	ds_read_b128 v[160:163], v5
	ds_read_b128 v[164:167], v5 offset:1024
	ds_read_b128 v[168:171], v5 offset:2048
	ds_read_b128 v[182:185], v5 offset:3072
	v_add_u32_e32 v5, s58, v177
	ds_read_b128 v[186:189], v5
	ds_read_b128 v[190:193], v5 offset:1024
	ds_read_b128 v[194:197], v5 offset:2048
	ds_read_b128 v[198:201], v5 offset:3072
	s_add_i32 m0, s46, 0xc000
	ds_read_b128 v[202:205], v180
	ds_read_b128 v[206:209], v180 offset:1024
	ds_read_b128 v[210:213], v180 offset:2048
	ds_read_b128 v[214:217], v180 offset:3072
	ds_read_b128 v[218:221], v180 offset:4096
	ds_read_b128 v[222:225], v180 offset:5120
	ds_read_b128 v[226:229], v180 offset:6144
	ds_read_b128 v[230:233], v180 offset:7168
	global_load_lds_dwordx4 v146, s[30:31]
	s_add_i32 m0, s46, 0xe000
	s_nop 0
	global_load_lds_dwordx4 v148, s[30:31]
	s_waitcnt vmcnt(8)
	s_waitcnt lgkmcnt(0)
	s_barrier
	s_setprio 1
	s_waitcnt lgkmcnt(0)
	v_mfma_i32_16x16x64_i8 v[132:135], v[160:163], v[202:205], v[132:135]
	v_mfma_i32_16x16x64_i8 v[128:131], v[168:171], v[202:205], v[128:131]
	v_mfma_i32_16x16x64_i8 v[124:127], v[160:163], v[210:213], v[124:127]
	v_mfma_i32_16x16x64_i8 v[120:123], v[168:171], v[210:213], v[120:123]
	v_mfma_i32_16x16x64_i8 v[112:115], v[160:163], v[218:221], v[112:115]
	v_mfma_i32_16x16x64_i8 v[104:107], v[168:171], v[218:221], v[104:107]
	v_mfma_i32_16x16x64_i8 v[96:99], v[160:163], v[226:229], v[96:99]
	v_mfma_i32_16x16x64_i8 v[88:91], v[168:171], v[226:229], v[88:91]
	v_mfma_i32_16x16x64_i8 v[132:135], v[164:167], v[206:209], v[132:135]
	v_mfma_i32_16x16x64_i8 v[128:131], v[182:185], v[206:209], v[128:131]
	v_mfma_i32_16x16x64_i8 v[124:127], v[164:167], v[214:217], v[124:127]
	v_mfma_i32_16x16x64_i8 v[120:123], v[182:185], v[214:217], v[120:123]
	v_mfma_i32_16x16x64_i8 v[112:115], v[164:167], v[222:225], v[112:115]
	v_mfma_i32_16x16x64_i8 v[104:107], v[182:185], v[222:225], v[104:107]
	v_mfma_i32_16x16x64_i8 v[96:99], v[164:167], v[230:233], v[96:99]
	v_mfma_i32_16x16x64_i8 v[88:91], v[182:185], v[230:233], v[88:91]
	s_setprio 0
	s_setprio 1
	v_mfma_i32_16x16x64_i8 v[116:119], v[186:189], v[202:205], v[116:119]
	v_mfma_i32_16x16x64_i8 v[108:111], v[194:197], v[202:205], v[108:111]
	v_mfma_i32_16x16x64_i8 v[100:103], v[186:189], v[210:213], v[100:103]
	v_mfma_i32_16x16x64_i8 v[92:95], v[194:197], v[210:213], v[92:95]
	v_mfma_i32_16x16x64_i8 v[84:87], v[186:189], v[218:221], v[84:87]
	v_mfma_i32_16x16x64_i8 v[80:83], v[194:197], v[218:221], v[80:83]
	v_mfma_i32_16x16x64_i8 v[76:79], v[186:189], v[226:229], v[76:79]
	v_mfma_i32_16x16x64_i8 v[72:75], v[194:197], v[226:229], v[72:75]
	v_mfma_i32_16x16x64_i8 v[116:119], v[190:193], v[206:209], v[116:119]
	v_mfma_i32_16x16x64_i8 v[108:111], v[198:201], v[206:209], v[108:111]
	v_mfma_i32_16x16x64_i8 v[100:103], v[190:193], v[214:217], v[100:103]
	v_mfma_i32_16x16x64_i8 v[92:95], v[198:201], v[214:217], v[92:95]
	v_mfma_i32_16x16x64_i8 v[84:87], v[190:193], v[222:225], v[84:87]
	v_mfma_i32_16x16x64_i8 v[80:83], v[198:201], v[222:225], v[80:83]
	v_mfma_i32_16x16x64_i8 v[76:79], v[190:193], v[230:233], v[76:79]
	v_mfma_i32_16x16x64_i8 v[72:75], v[198:201], v[230:233], v[72:75]
	s_setprio 0
	s_barrier
	s_add_i32 s74, s57, s45
	s_mov_b32 m0, s74
	ds_read_b128 v[202:205], v180 offset:16384
	ds_read_b128 v[206:209], v180 offset:17408
	ds_read_b128 v[210:213], v180 offset:18432
	ds_read_b128 v[214:217], v180 offset:19456
	ds_read_b128 v[218:221], v180 offset:20480
	ds_read_b128 v[222:225], v180 offset:21504
	ds_read_b128 v[226:229], v180 offset:22528
	ds_read_b128 v[230:233], v180 offset:23552
	global_load_lds_dwordx4 v138, s[34:35]
	s_add_i32 m0, s74, 0x2000
	s_add_u32 s74, s34, 0x80000
	s_addc_u32 s75, s35, 0
	s_add_i32 s76, s58, s45
	global_load_lds_dwordx4 v142, s[34:35]
	s_mov_b32 m0, s76
	s_nop 0
	global_load_lds_dwordx4 v138, s[74:75]
	s_add_i32 m0, s76, 0x2000
	s_nop 0
	global_load_lds_dwordx4 v142, s[74:75]
	s_mov_b32 m0, s46
	s_nop 0
	global_load_lds_dwordx4 v136, s[36:37]
	s_mov_b32 m0, s47
	s_nop 0
	global_load_lds_dwordx4 v140, s[36:37]
	s_waitcnt vmcnt(8)
	s_waitcnt lgkmcnt(0)
	s_barrier
	s_setprio 1
	s_waitcnt lgkmcnt(0)
	v_mfma_i32_16x16x64_i8 v[68:71], v[160:163], v[202:205], v[68:71]
	v_mfma_i32_16x16x64_i8 v[64:67], v[168:171], v[202:205], v[64:67]
	v_mfma_i32_16x16x64_i8 v[60:63], v[160:163], v[210:213], v[60:63]
	v_mfma_i32_16x16x64_i8 v[56:59], v[168:171], v[210:213], v[56:59]
	v_mfma_i32_16x16x64_i8 v[48:51], v[160:163], v[218:221], v[48:51]
	v_mfma_i32_16x16x64_i8 v[40:43], v[168:171], v[218:221], v[40:43]
	v_mfma_i32_16x16x64_i8 v[32:35], v[160:163], v[226:229], v[32:35]
	v_mfma_i32_16x16x64_i8 v[24:27], v[168:171], v[226:229], v[24:27]
	v_mfma_i32_16x16x64_i8 v[68:71], v[164:167], v[206:209], v[68:71]
	v_mfma_i32_16x16x64_i8 v[64:67], v[182:185], v[206:209], v[64:67]
	v_mfma_i32_16x16x64_i8 v[60:63], v[164:167], v[214:217], v[60:63]
	v_mfma_i32_16x16x64_i8 v[56:59], v[182:185], v[214:217], v[56:59]
	v_mfma_i32_16x16x64_i8 v[48:51], v[164:167], v[222:225], v[48:51]
	v_mfma_i32_16x16x64_i8 v[40:43], v[182:185], v[222:225], v[40:43]
	v_mfma_i32_16x16x64_i8 v[32:35], v[164:167], v[230:233], v[32:35]
	v_mfma_i32_16x16x64_i8 v[24:27], v[182:185], v[230:233], v[24:27]
	s_setprio 0
	s_setprio 1
	v_mfma_i32_16x16x64_i8 v[52:55], v[186:189], v[202:205], v[52:55]
	v_mfma_i32_16x16x64_i8 v[44:47], v[194:197], v[202:205], v[44:47]
	v_mfma_i32_16x16x64_i8 v[36:39], v[186:189], v[210:213], v[36:39]
	v_mfma_i32_16x16x64_i8 v[28:31], v[194:197], v[210:213], v[28:31]
	v_mfma_i32_16x16x64_i8 v[20:23], v[186:189], v[218:221], v[20:23]
	v_mfma_i32_16x16x64_i8 v[16:19], v[194:197], v[218:221], v[16:19]
	v_mfma_i32_16x16x64_i8 v[12:15], v[186:189], v[226:229], v[12:15]
	v_mfma_i32_16x16x64_i8 v[6:9], v[194:197], v[226:229], v[8:11]
	v_mfma_i32_16x16x64_i8 v[52:55], v[190:193], v[206:209], v[52:55]
	v_mfma_i32_16x16x64_i8 v[44:47], v[198:201], v[206:209], v[44:47]
	v_mfma_i32_16x16x64_i8 v[36:39], v[190:193], v[214:217], v[36:39]
	v_mfma_i32_16x16x64_i8 v[28:31], v[198:201], v[214:217], v[28:31]
	v_mfma_i32_16x16x64_i8 v[20:23], v[190:193], v[222:225], v[20:23]
	v_mfma_i32_16x16x64_i8 v[16:19], v[198:201], v[222:225], v[16:19]
	v_mfma_i32_16x16x64_i8 v[12:15], v[190:193], v[230:233], v[12:15]
	v_mfma_i32_16x16x64_i8 v[6:9], v[198:201], v[230:233], v[6:9]
	s_setprio 0
	s_barrier
	s_add_i32 s74, 0, 0x18000
	v_add_u32_e32 v5, s74, v177
	s_add_i32 s75, 0, 0x1c000
	ds_read_b128 v[160:163], v5
	ds_read_b128 v[164:167], v5 offset:1024
	ds_read_b128 v[168:171], v5 offset:2048
	ds_read_b128 v[182:185], v5 offset:3072
	v_add_u32_e32 v5, s75, v177
	ds_read_b128 v[186:189], v5
	ds_read_b128 v[190:193], v5 offset:1024
	ds_read_b128 v[194:197], v5 offset:2048
	ds_read_b128 v[198:201], v5 offset:3072
	s_add_u32 s36, s36, 0x80000
	s_addc_u32 s37, s37, 0
	s_mov_b32 m0, s48
	ds_read_b128 v[202:205], v180 offset:32768
	ds_read_b128 v[206:209], v180 offset:33792
	ds_read_b128 v[210:213], v180 offset:34816
	ds_read_b128 v[214:217], v180 offset:35840
	ds_read_b128 v[218:221], v180 offset:36864
	ds_read_b128 v[222:225], v180 offset:37888
	ds_read_b128 v[226:229], v180 offset:38912
	ds_read_b128 v[230:233], v180 offset:39936
	global_load_lds_dwordx4 v136, s[36:37]
	s_mov_b32 m0, s49
	s_nop 0
	global_load_lds_dwordx4 v140, s[36:37]
	s_waitcnt vmcnt(8)
	s_waitcnt lgkmcnt(0)
	s_barrier
	s_setprio 1
	s_waitcnt lgkmcnt(0)
	v_mfma_i32_16x16x64_i8 v[132:135], v[160:163], v[202:205], v[132:135]
	v_mfma_i32_16x16x64_i8 v[128:131], v[168:171], v[202:205], v[128:131]
	v_mfma_i32_16x16x64_i8 v[124:127], v[160:163], v[210:213], v[124:127]
	v_mfma_i32_16x16x64_i8 v[120:123], v[168:171], v[210:213], v[120:123]
	v_mfma_i32_16x16x64_i8 v[112:115], v[160:163], v[218:221], v[112:115]
	v_mfma_i32_16x16x64_i8 v[104:107], v[168:171], v[218:221], v[104:107]
	v_mfma_i32_16x16x64_i8 v[96:99], v[160:163], v[226:229], v[96:99]
	v_mfma_i32_16x16x64_i8 v[88:91], v[168:171], v[226:229], v[88:91]
	v_mfma_i32_16x16x64_i8 v[132:135], v[164:167], v[206:209], v[132:135]
	v_mfma_i32_16x16x64_i8 v[128:131], v[182:185], v[206:209], v[128:131]
	v_mfma_i32_16x16x64_i8 v[124:127], v[164:167], v[214:217], v[124:127]
	v_mfma_i32_16x16x64_i8 v[120:123], v[182:185], v[214:217], v[120:123]
	v_mfma_i32_16x16x64_i8 v[112:115], v[164:167], v[222:225], v[112:115]
	v_mfma_i32_16x16x64_i8 v[104:107], v[182:185], v[222:225], v[104:107]
	v_mfma_i32_16x16x64_i8 v[96:99], v[164:167], v[230:233], v[96:99]
	v_mfma_i32_16x16x64_i8 v[88:91], v[182:185], v[230:233], v[88:91]
	s_setprio 0
	s_setprio 1
	v_mfma_i32_16x16x64_i8 v[116:119], v[186:189], v[202:205], v[116:119]
	v_mfma_i32_16x16x64_i8 v[108:111], v[194:197], v[202:205], v[108:111]
	v_mfma_i32_16x16x64_i8 v[100:103], v[186:189], v[210:213], v[100:103]
	v_mfma_i32_16x16x64_i8 v[92:95], v[194:197], v[210:213], v[92:95]
	v_mfma_i32_16x16x64_i8 v[84:87], v[186:189], v[218:221], v[84:87]
	v_mfma_i32_16x16x64_i8 v[80:83], v[194:197], v[218:221], v[80:83]
	v_mfma_i32_16x16x64_i8 v[76:79], v[186:189], v[226:229], v[76:79]
	v_mfma_i32_16x16x64_i8 v[72:75], v[194:197], v[226:229], v[72:75]
	v_mfma_i32_16x16x64_i8 v[116:119], v[190:193], v[206:209], v[116:119]
	v_mfma_i32_16x16x64_i8 v[108:111], v[198:201], v[206:209], v[108:111]
	v_mfma_i32_16x16x64_i8 v[100:103], v[190:193], v[214:217], v[100:103]
	v_mfma_i32_16x16x64_i8 v[92:95], v[198:201], v[214:217], v[92:95]
	v_mfma_i32_16x16x64_i8 v[84:87], v[190:193], v[222:225], v[84:87]
	v_mfma_i32_16x16x64_i8 v[80:83], v[198:201], v[222:225], v[80:83]
	v_mfma_i32_16x16x64_i8 v[76:79], v[190:193], v[230:233], v[76:79]
	v_mfma_i32_16x16x64_i8 v[72:75], v[198:201], v[230:233], v[72:75]
	s_setprio 0
	s_barrier
	s_add_u32 s98, s34, s14
	s_addc_u32 s99, s35, s15
	s_add_u32 s100, s36, s14
	s_addc_u32 s101, s37, s15
	s_sub_u32 s100, s100, 0x80000
	s_subb_u32 s101, s101, 0
	s_add_i32 s36, s74, s45
	s_mov_b32 m0, s36
	ds_read_b128 v[152:155], v180 offset:49152
	ds_read_b128 v[156:159], v180 offset:50176
	ds_read_b128 v[202:205], v180 offset:51200
	ds_read_b128 v[206:209], v180 offset:52224
	ds_read_b128 v[210:213], v180 offset:53248
	ds_read_b128 v[214:217], v180 offset:54272
	ds_read_b128 v[218:221], v180 offset:55296
	ds_read_b128 v[222:225], v180 offset:56320
	global_load_lds_dwordx4 v138, s[98:99]
	s_add_i32 m0, s36, 0x2000
	s_add_u32 s34, s34, 0x80080
	s_addc_u32 s35, s35, 0
	s_add_i32 s36, s75, s45
	global_load_lds_dwordx4 v142, s[98:99]
	s_mov_b32 m0, s36
	s_nop 0
	global_load_lds_dwordx4 v138, s[34:35]
	s_add_i32 m0, s36, 0x2000
	s_nop 0
	global_load_lds_dwordx4 v142, s[34:35]
	s_mov_b32 m0, s54
	s_nop 0
	global_load_lds_dwordx4 v136, s[100:101]
	s_mov_b32 m0, s55
	s_nop 0
	global_load_lds_dwordx4 v140, s[100:101]
	s_waitcnt vmcnt(8)
	s_waitcnt lgkmcnt(0)
	s_barrier
	s_setprio 1
	s_waitcnt lgkmcnt(0)
	v_mfma_i32_16x16x64_i8 v[68:71], v[160:163], v[152:155], v[68:71]
	v_mfma_i32_16x16x64_i8 v[64:67], v[168:171], v[152:155], v[64:67]
	v_mfma_i32_16x16x64_i8 v[60:63], v[160:163], v[202:205], v[60:63]
	v_mfma_i32_16x16x64_i8 v[56:59], v[168:171], v[202:205], v[56:59]
	v_mfma_i32_16x16x64_i8 v[48:51], v[160:163], v[210:213], v[48:51]
	v_mfma_i32_16x16x64_i8 v[40:43], v[168:171], v[210:213], v[40:43]
	v_mfma_i32_16x16x64_i8 v[32:35], v[160:163], v[218:221], v[32:35]
	v_mfma_i32_16x16x64_i8 v[24:27], v[168:171], v[218:221], v[24:27]
	v_mfma_i32_16x16x64_i8 v[68:71], v[164:167], v[156:159], v[68:71]
	v_mfma_i32_16x16x64_i8 v[64:67], v[182:185], v[156:159], v[64:67]
	v_mfma_i32_16x16x64_i8 v[60:63], v[164:167], v[206:209], v[60:63]
	v_mfma_i32_16x16x64_i8 v[56:59], v[182:185], v[206:209], v[56:59]
	v_mfma_i32_16x16x64_i8 v[48:51], v[164:167], v[214:217], v[48:51]
	v_mfma_i32_16x16x64_i8 v[40:43], v[182:185], v[214:217], v[40:43]
	v_mfma_i32_16x16x64_i8 v[32:35], v[164:167], v[222:225], v[32:35]
	v_mfma_i32_16x16x64_i8 v[24:27], v[182:185], v[222:225], v[24:27]
	s_setprio 0
	s_setprio 1
	v_mfma_i32_16x16x64_i8 v[52:55], v[186:189], v[152:155], v[52:55]
	v_mfma_i32_16x16x64_i8 v[44:47], v[194:197], v[152:155], v[44:47]
	v_mfma_i32_16x16x64_i8 v[36:39], v[186:189], v[202:205], v[36:39]
	v_mfma_i32_16x16x64_i8 v[28:31], v[194:197], v[202:205], v[28:31]
	v_mfma_i32_16x16x64_i8 v[20:23], v[186:189], v[210:213], v[20:23]
	v_mfma_i32_16x16x64_i8 v[16:19], v[194:197], v[210:213], v[16:19]
	v_mfma_i32_16x16x64_i8 v[10:13], v[186:189], v[218:221], v[12:15]
	v_mfma_i32_16x16x64_i8 v[6:9], v[194:197], v[218:221], v[6:9]
	v_mfma_i32_16x16x64_i8 v[52:55], v[190:193], v[156:159], v[52:55]
	v_mfma_i32_16x16x64_i8 v[44:47], v[198:201], v[156:159], v[44:47]
	v_mfma_i32_16x16x64_i8 v[36:39], v[190:193], v[206:209], v[36:39]
	v_mfma_i32_16x16x64_i8 v[28:31], v[198:201], v[206:209], v[28:31]
	v_mfma_i32_16x16x64_i8 v[20:23], v[190:193], v[214:217], v[20:23]
	v_mfma_i32_16x16x64_i8 v[16:19], v[198:201], v[214:217], v[16:19]
	v_mfma_i32_16x16x64_i8 v[12:15], v[190:193], v[222:225], v[10:13]
	v_mfma_i32_16x16x64_i8 v[8:11], v[198:201], v[222:225], v[6:9]
	s_setprio 0
	s_barrier
	s_add_u32 s30, s30, 0x100
	s_addc_u32 s31, s31, 0
	s_add_u32 s72, s72, 0x100
	s_addc_u32 s73, s73, 0
	s_cmp_ge_i32 s8, s66
	s_cbranch_scc0 .Lp1i_top
	s_branch .Lp1i_epi

.LBB0_327:
	s_add_i32 s8, s74, 2
	s_add_u32 s34, s30, 0xfff80080
	s_addc_u32 s35, s31, -1
	s_cmp_eq_u32 s71, s74
	s_cselect_b32 s37, s67, s35
	s_cselect_b32 s36, s68, s34
	s_cselect_b32 s35, s69, s73
	s_cselect_b32 s34, s70, s72
	s_cmpk_lt_i32 s3, 0x56
	s_cselect_b32 s74, s56, 0x2b00
	s_mov_b32 s75, 0xac00
	s_cselect_b32 s76, s75, 0x4000
	s_sub_i32 s74, s74, s33
	v_min3_i32 v5, s74, v174, 2
	v_sub_u32_e32 v174, v174, v5
	v_readfirstlane_b32 s78, v5
	s_max_i32 s74, s78, 0
	s_add_i32 s74, s33, s74
	s_add_i32 s77, s74, -1
	s_min_i32 s74, s33, s77
	s_mul_hi_i32 s75, s76, s74
	s_mul_i32 s74, s76, s74
	s_add_u32 s74, s38, s74
	s_addc_u32 s75, s39, s75
	s_mul_hi_i32 s79, s76, s77
	s_mul_i32 s76, s76, s77
	s_add_u32 s76, s38, s76
	global_load_dwordx4 v[152:155], v173, s[74:75] nt
	s_addc_u32 s77, s39, s79
	global_load_dwordx4 v[156:159], v173, s[76:77] nt
	s_add_i32 s33, s78, s33
	v_add_u32_e32 v5, s57, v177
	ds_read_b128 v[160:163], v5
	ds_read_b128 v[164:167], v5 offset:1024
	ds_read_b128 v[168:171], v5 offset:2048
	ds_read_b128 v[182:185], v5 offset:3072
	v_add_u32_e32 v5, s58, v177
	ds_read_b128 v[186:189], v5
	ds_read_b128 v[190:193], v5 offset:1024
	ds_read_b128 v[194:197], v5 offset:2048
	ds_read_b128 v[198:201], v5 offset:3072
	s_add_i32 m0, s46, 0xc000
	ds_read_b128 v[202:205], v180
	ds_read_b128 v[206:209], v180 offset:1024
	ds_read_b128 v[210:213], v180 offset:2048
	ds_read_b128 v[214:217], v180 offset:3072
	ds_read_b128 v[218:221], v180 offset:4096
	ds_read_b128 v[222:225], v180 offset:5120
	ds_read_b128 v[226:229], v180 offset:6144
	ds_read_b128 v[230:233], v180 offset:7168
	global_load_lds_dwordx4 v146, s[30:31]
	s_add_i32 m0, s46, 0xe000
	s_nop 0
	global_load_lds_dwordx4 v148, s[30:31]
	s_waitcnt vmcnt(10)
	s_waitcnt lgkmcnt(0)
	s_barrier
	s_setprio 1
	s_waitcnt lgkmcnt(0)
	v_mfma_i32_16x16x64_i8 v[132:135], v[160:163], v[202:205], v[132:135]
	v_mfma_i32_16x16x64_i8 v[128:131], v[168:171], v[202:205], v[128:131]
	v_mfma_i32_16x16x64_i8 v[124:127], v[160:163], v[210:213], v[124:127]
	v_mfma_i32_16x16x64_i8 v[120:123], v[168:171], v[210:213], v[120:123]
	v_mfma_i32_16x16x64_i8 v[112:115], v[160:163], v[218:221], v[112:115]
	v_mfma_i32_16x16x64_i8 v[104:107], v[168:171], v[218:221], v[104:107]
	v_mfma_i32_16x16x64_i8 v[96:99], v[160:163], v[226:229], v[96:99]
	v_mfma_i32_16x16x64_i8 v[88:91], v[168:171], v[226:229], v[88:91]
	v_mfma_i32_16x16x64_i8 v[132:135], v[164:167], v[206:209], v[132:135]
	v_mfma_i32_16x16x64_i8 v[128:131], v[182:185], v[206:209], v[128:131]
	v_mfma_i32_16x16x64_i8 v[124:127], v[164:167], v[214:217], v[124:127]
	v_mfma_i32_16x16x64_i8 v[120:123], v[182:185], v[214:217], v[120:123]
	v_mfma_i32_16x16x64_i8 v[112:115], v[164:167], v[222:225], v[112:115]
	v_mfma_i32_16x16x64_i8 v[104:107], v[182:185], v[222:225], v[104:107]
	v_mfma_i32_16x16x64_i8 v[96:99], v[164:167], v[230:233], v[96:99]
	v_mfma_i32_16x16x64_i8 v[88:91], v[182:185], v[230:233], v[88:91]
	s_setprio 0
	s_setprio 1
	v_mfma_i32_16x16x64_i8 v[116:119], v[186:189], v[202:205], v[116:119]
	v_mfma_i32_16x16x64_i8 v[108:111], v[194:197], v[202:205], v[108:111]
	v_mfma_i32_16x16x64_i8 v[100:103], v[186:189], v[210:213], v[100:103]
	v_mfma_i32_16x16x64_i8 v[92:95], v[194:197], v[210:213], v[92:95]
	v_mfma_i32_16x16x64_i8 v[84:87], v[186:189], v[218:221], v[84:87]
	v_mfma_i32_16x16x64_i8 v[80:83], v[194:197], v[218:221], v[80:83]
	v_mfma_i32_16x16x64_i8 v[76:79], v[186:189], v[226:229], v[76:79]
	v_mfma_i32_16x16x64_i8 v[72:75], v[194:197], v[226:229], v[72:75]
	v_mfma_i32_16x16x64_i8 v[116:119], v[190:193], v[206:209], v[116:119]
	v_mfma_i32_16x16x64_i8 v[108:111], v[198:201], v[206:209], v[108:111]
	v_mfma_i32_16x16x64_i8 v[100:103], v[190:193], v[214:217], v[100:103]
	v_mfma_i32_16x16x64_i8 v[92:95], v[198:201], v[214:217], v[92:95]
	v_mfma_i32_16x16x64_i8 v[84:87], v[190:193], v[222:225], v[84:87]
	v_mfma_i32_16x16x64_i8 v[80:83], v[198:201], v[222:225], v[80:83]
	v_mfma_i32_16x16x64_i8 v[76:79], v[190:193], v[230:233], v[76:79]
	v_mfma_i32_16x16x64_i8 v[72:75], v[198:201], v[230:233], v[72:75]
	s_setprio 0
	s_barrier
	s_add_i32 s74, s57, s45
	s_mov_b32 m0, s74
	ds_read_b128 v[202:205], v180 offset:16384
	ds_read_b128 v[206:209], v180 offset:17408
	ds_read_b128 v[210:213], v180 offset:18432
	ds_read_b128 v[214:217], v180 offset:19456
	ds_read_b128 v[218:221], v180 offset:20480
	ds_read_b128 v[222:225], v180 offset:21504
	ds_read_b128 v[226:229], v180 offset:22528
	ds_read_b128 v[230:233], v180 offset:23552
	global_load_lds_dwordx4 v138, s[34:35]
	s_add_i32 m0, s74, 0x2000
	s_add_u32 s74, s34, 0x80000
	s_addc_u32 s75, s35, 0
	s_add_i32 s76, s58, s45
	global_load_lds_dwordx4 v142, s[34:35]
	s_mov_b32 m0, s76
	s_nop 0
	global_load_lds_dwordx4 v138, s[74:75]
	s_add_i32 m0, s76, 0x2000
	s_nop 0
	global_load_lds_dwordx4 v142, s[74:75]
	s_mov_b32 m0, s46
	s_nop 0
	global_load_lds_dwordx4 v136, s[36:37]
	s_mov_b32 m0, s47
	s_nop 0
	global_load_lds_dwordx4 v140, s[36:37]
	s_waitcnt vmcnt(10)
	s_waitcnt lgkmcnt(0)
	s_barrier
	s_setprio 1
	s_waitcnt lgkmcnt(0)
	v_mfma_i32_16x16x64_i8 v[68:71], v[160:163], v[202:205], v[68:71]
	v_mfma_i32_16x16x64_i8 v[64:67], v[168:171], v[202:205], v[64:67]
	v_mfma_i32_16x16x64_i8 v[60:63], v[160:163], v[210:213], v[60:63]
	v_mfma_i32_16x16x64_i8 v[56:59], v[168:171], v[210:213], v[56:59]
	v_mfma_i32_16x16x64_i8 v[48:51], v[160:163], v[218:221], v[48:51]
	v_mfma_i32_16x16x64_i8 v[40:43], v[168:171], v[218:221], v[40:43]
	v_mfma_i32_16x16x64_i8 v[32:35], v[160:163], v[226:229], v[32:35]
	v_mfma_i32_16x16x64_i8 v[24:27], v[168:171], v[226:229], v[24:27]
	v_mfma_i32_16x16x64_i8 v[68:71], v[164:167], v[206:209], v[68:71]
	v_mfma_i32_16x16x64_i8 v[64:67], v[182:185], v[206:209], v[64:67]
	v_mfma_i32_16x16x64_i8 v[60:63], v[164:167], v[214:217], v[60:63]
	v_mfma_i32_16x16x64_i8 v[56:59], v[182:185], v[214:217], v[56:59]
	v_mfma_i32_16x16x64_i8 v[48:51], v[164:167], v[222:225], v[48:51]
	v_mfma_i32_16x16x64_i8 v[40:43], v[182:185], v[222:225], v[40:43]
	v_mfma_i32_16x16x64_i8 v[32:35], v[164:167], v[230:233], v[32:35]
	v_mfma_i32_16x16x64_i8 v[24:27], v[182:185], v[230:233], v[24:27]
	s_setprio 0
	s_setprio 1
	v_mfma_i32_16x16x64_i8 v[52:55], v[186:189], v[202:205], v[52:55]
	v_mfma_i32_16x16x64_i8 v[44:47], v[194:197], v[202:205], v[44:47]
	v_mfma_i32_16x16x64_i8 v[36:39], v[186:189], v[210:213], v[36:39]
	v_mfma_i32_16x16x64_i8 v[28:31], v[194:197], v[210:213], v[28:31]
	v_mfma_i32_16x16x64_i8 v[20:23], v[186:189], v[218:221], v[20:23]
	v_mfma_i32_16x16x64_i8 v[16:19], v[194:197], v[218:221], v[16:19]
	v_mfma_i32_16x16x64_i8 v[12:15], v[186:189], v[226:229], v[12:15]
	v_mfma_i32_16x16x64_i8 v[6:9], v[194:197], v[226:229], v[8:11]
	v_mfma_i32_16x16x64_i8 v[52:55], v[190:193], v[206:209], v[52:55]
	v_mfma_i32_16x16x64_i8 v[44:47], v[198:201], v[206:209], v[44:47]
	v_mfma_i32_16x16x64_i8 v[36:39], v[190:193], v[214:217], v[36:39]
	v_mfma_i32_16x16x64_i8 v[28:31], v[198:201], v[214:217], v[28:31]
	v_mfma_i32_16x16x64_i8 v[20:23], v[190:193], v[222:225], v[20:23]
	v_mfma_i32_16x16x64_i8 v[16:19], v[198:201], v[222:225], v[16:19]
	v_mfma_i32_16x16x64_i8 v[12:15], v[190:193], v[230:233], v[12:15]
	v_mfma_i32_16x16x64_i8 v[6:9], v[198:201], v[230:233], v[6:9]
	s_setprio 0
	s_barrier
	s_add_i32 s74, 0, 0x18000
	v_add_u32_e32 v5, s74, v177
	s_add_i32 s75, 0, 0x1c000
	ds_read_b128 v[160:163], v5
	ds_read_b128 v[164:167], v5 offset:1024
	ds_read_b128 v[168:171], v5 offset:2048
	ds_read_b128 v[182:185], v5 offset:3072
	v_add_u32_e32 v5, s75, v177
	ds_read_b128 v[186:189], v5
	ds_read_b128 v[190:193], v5 offset:1024
	ds_read_b128 v[194:197], v5 offset:2048
	ds_read_b128 v[198:201], v5 offset:3072
	s_add_u32 s36, s36, 0x80000
	s_addc_u32 s37, s37, 0
	s_mov_b32 m0, s48
	ds_read_b128 v[202:205], v180 offset:32768
	ds_read_b128 v[206:209], v180 offset:33792
	ds_read_b128 v[210:213], v180 offset:34816
	ds_read_b128 v[214:217], v180 offset:35840
	ds_read_b128 v[218:221], v180 offset:36864
	ds_read_b128 v[222:225], v180 offset:37888
	ds_read_b128 v[226:229], v180 offset:38912
	ds_read_b128 v[230:233], v180 offset:39936
	global_load_lds_dwordx4 v136, s[36:37]
	s_mov_b32 m0, s49
	s_nop 0
	global_load_lds_dwordx4 v140, s[36:37]
	s_waitcnt vmcnt(8)
	s_waitcnt lgkmcnt(0)
	s_barrier
	s_setprio 1
	s_waitcnt lgkmcnt(0)
	v_mfma_i32_16x16x64_i8 v[132:135], v[160:163], v[202:205], v[132:135]
	v_mfma_i32_16x16x64_i8 v[128:131], v[168:171], v[202:205], v[128:131]
	v_mfma_i32_16x16x64_i8 v[124:127], v[160:163], v[210:213], v[124:127]
	v_mfma_i32_16x16x64_i8 v[120:123], v[168:171], v[210:213], v[120:123]
	v_mfma_i32_16x16x64_i8 v[112:115], v[160:163], v[218:221], v[112:115]
	v_max3_f32 v0, v0, |v152|, |v156|
	v_mfma_i32_16x16x64_i8 v[104:107], v[168:171], v[218:221], v[104:107]
	v_max3_f32 v1, v1, |v153|, |v157|
	v_mfma_i32_16x16x64_i8 v[96:99], v[160:163], v[226:229], v[96:99]
	v_max3_f32 v2, v2, |v154|, |v158|
	v_mfma_i32_16x16x64_i8 v[88:91], v[168:171], v[226:229], v[88:91]
	v_max3_f32 v3, v3, |v155|, |v159|
	v_mfma_i32_16x16x64_i8 v[132:135], v[164:167], v[206:209], v[132:135]
	v_mfma_i32_16x16x64_i8 v[128:131], v[182:185], v[206:209], v[128:131]
	v_mfma_i32_16x16x64_i8 v[124:127], v[164:167], v[214:217], v[124:127]
	v_mfma_i32_16x16x64_i8 v[120:123], v[182:185], v[214:217], v[120:123]
	v_mfma_i32_16x16x64_i8 v[112:115], v[164:167], v[222:225], v[112:115]
	v_mfma_i32_16x16x64_i8 v[104:107], v[182:185], v[222:225], v[104:107]
	v_mfma_i32_16x16x64_i8 v[96:99], v[164:167], v[230:233], v[96:99]
	v_mfma_i32_16x16x64_i8 v[88:91], v[182:185], v[230:233], v[88:91]
	s_setprio 0
	s_setprio 1
	v_mfma_i32_16x16x64_i8 v[116:119], v[186:189], v[202:205], v[116:119]
	v_mfma_i32_16x16x64_i8 v[108:111], v[194:197], v[202:205], v[108:111]
	v_mfma_i32_16x16x64_i8 v[100:103], v[186:189], v[210:213], v[100:103]
	v_mfma_i32_16x16x64_i8 v[92:95], v[194:197], v[210:213], v[92:95]
	v_mfma_i32_16x16x64_i8 v[84:87], v[186:189], v[218:221], v[84:87]
	v_mfma_i32_16x16x64_i8 v[80:83], v[194:197], v[218:221], v[80:83]
	v_mfma_i32_16x16x64_i8 v[76:79], v[186:189], v[226:229], v[76:79]
	v_mfma_i32_16x16x64_i8 v[72:75], v[194:197], v[226:229], v[72:75]
	v_mfma_i32_16x16x64_i8 v[116:119], v[190:193], v[206:209], v[116:119]
	v_mfma_i32_16x16x64_i8 v[108:111], v[198:201], v[206:209], v[108:111]
	v_mfma_i32_16x16x64_i8 v[100:103], v[190:193], v[214:217], v[100:103]
	v_mfma_i32_16x16x64_i8 v[92:95], v[198:201], v[214:217], v[92:95]
	v_mfma_i32_16x16x64_i8 v[84:87], v[190:193], v[222:225], v[84:87]
	v_mfma_i32_16x16x64_i8 v[80:83], v[198:201], v[222:225], v[80:83]
	v_mfma_i32_16x16x64_i8 v[76:79], v[190:193], v[230:233], v[76:79]
	v_mfma_i32_16x16x64_i8 v[72:75], v[198:201], v[230:233], v[72:75]
	s_setprio 0
	s_barrier
	s_add_u32 s98, s34, s14
	s_addc_u32 s99, s35, s15
	s_add_u32 s100, s36, s14
	s_addc_u32 s101, s37, s15
	s_sub_u32 s100, s100, 0x80000
	s_subb_u32 s101, s101, 0
	s_add_i32 s36, s74, s45
	s_mov_b32 m0, s36
	ds_read_b128 v[152:155], v180 offset:49152
	ds_read_b128 v[156:159], v180 offset:50176
	ds_read_b128 v[202:205], v180 offset:51200
	ds_read_b128 v[206:209], v180 offset:52224
	ds_read_b128 v[210:213], v180 offset:53248
	ds_read_b128 v[214:217], v180 offset:54272
	ds_read_b128 v[218:221], v180 offset:55296
	ds_read_b128 v[222:225], v180 offset:56320
	global_load_lds_dwordx4 v138, s[98:99]
	s_add_i32 m0, s36, 0x2000
	s_add_u32 s34, s34, 0x80080
	s_addc_u32 s35, s35, 0
	s_add_i32 s36, s75, s45
	global_load_lds_dwordx4 v142, s[98:99]
	s_mov_b32 m0, s36
	s_nop 0
	global_load_lds_dwordx4 v138, s[34:35]
	s_add_i32 m0, s36, 0x2000
	s_nop 0
	global_load_lds_dwordx4 v142, s[34:35]
	s_mov_b32 m0, s54
	s_nop 0
	global_load_lds_dwordx4 v136, s[100:101]
	s_mov_b32 m0, s55
	s_nop 0
	global_load_lds_dwordx4 v140, s[100:101]
	s_waitcnt vmcnt(8)
	s_waitcnt lgkmcnt(0)
	s_barrier
	s_setprio 1
	s_waitcnt lgkmcnt(0)
	v_mfma_i32_16x16x64_i8 v[68:71], v[160:163], v[152:155], v[68:71]
	v_mfma_i32_16x16x64_i8 v[64:67], v[168:171], v[152:155], v[64:67]
	v_mfma_i32_16x16x64_i8 v[60:63], v[160:163], v[202:205], v[60:63]
	v_mfma_i32_16x16x64_i8 v[56:59], v[168:171], v[202:205], v[56:59]
	v_mfma_i32_16x16x64_i8 v[48:51], v[160:163], v[210:213], v[48:51]
	v_mfma_i32_16x16x64_i8 v[40:43], v[168:171], v[210:213], v[40:43]
	v_mfma_i32_16x16x64_i8 v[32:35], v[160:163], v[218:221], v[32:35]
	v_mfma_i32_16x16x64_i8 v[24:27], v[168:171], v[218:221], v[24:27]
	v_mfma_i32_16x16x64_i8 v[68:71], v[164:167], v[156:159], v[68:71]
	v_mfma_i32_16x16x64_i8 v[64:67], v[182:185], v[156:159], v[64:67]
	v_mfma_i32_16x16x64_i8 v[60:63], v[164:167], v[206:209], v[60:63]
	v_mfma_i32_16x16x64_i8 v[56:59], v[182:185], v[206:209], v[56:59]
	v_mfma_i32_16x16x64_i8 v[48:51], v[164:167], v[214:217], v[48:51]
	v_mfma_i32_16x16x64_i8 v[40:43], v[182:185], v[214:217], v[40:43]
	v_mfma_i32_16x16x64_i8 v[32:35], v[164:167], v[222:225], v[32:35]
	v_mfma_i32_16x16x64_i8 v[24:27], v[182:185], v[222:225], v[24:27]
	s_setprio 0
	s_setprio 1
	v_mfma_i32_16x16x64_i8 v[52:55], v[186:189], v[152:155], v[52:55]
	v_mfma_i32_16x16x64_i8 v[44:47], v[194:197], v[152:155], v[44:47]
	v_mfma_i32_16x16x64_i8 v[36:39], v[186:189], v[202:205], v[36:39]
	v_mfma_i32_16x16x64_i8 v[28:31], v[194:197], v[202:205], v[28:31]
	v_mfma_i32_16x16x64_i8 v[20:23], v[186:189], v[210:213], v[20:23]
	v_mfma_i32_16x16x64_i8 v[16:19], v[194:197], v[210:213], v[16:19]
	v_mfma_i32_16x16x64_i8 v[10:13], v[186:189], v[218:221], v[12:15]
	v_mfma_i32_16x16x64_i8 v[6:9], v[194:197], v[218:221], v[6:9]
	v_mfma_i32_16x16x64_i8 v[52:55], v[190:193], v[156:159], v[52:55]
	v_mfma_i32_16x16x64_i8 v[44:47], v[198:201], v[156:159], v[44:47]
	v_mfma_i32_16x16x64_i8 v[36:39], v[190:193], v[206:209], v[36:39]
	v_mfma_i32_16x16x64_i8 v[28:31], v[198:201], v[206:209], v[28:31]
	v_mfma_i32_16x16x64_i8 v[20:23], v[190:193], v[214:217], v[20:23]
	v_mfma_i32_16x16x64_i8 v[16:19], v[198:201], v[214:217], v[16:19]
	v_mfma_i32_16x16x64_i8 v[12:15], v[190:193], v[222:225], v[10:13]
	v_mfma_i32_16x16x64_i8 v[8:11], v[198:201], v[222:225], v[6:9]
	s_setprio 0
	s_barrier
	s_add_u32 s30, s30, 0x100
	s_addc_u32 s31, s31, 0
	s_add_u32 s72, s72, 0x100
	s_addc_u32 s73, s73, 0
	s_cmp_ge_i32 s8, s66
	s_cbranch_scc0 .LBB0_312

.Lp4_body:
	s_add_i32 s8, s71, 2
	s_add_u32 s28, s26, 0xfff00080
	s_addc_u32 s29, s27, -1
	s_cmp_eq_u32 s68, s71
	s_cselect_b32 s31, s64, s29
	s_cselect_b32 s30, s65, s28
	s_cselect_b32 s29, s66, s70
	s_cselect_b32 s28, s67, s69
	v_add_u32_e32 v5, s53, v163
	ds_read_b128 v[172:175], v5
	ds_read_b128 v[176:179], v5 offset:1024
	ds_read_b128 v[180:183], v5 offset:2048
	ds_read_b128 v[184:187], v5 offset:3072
	v_add_u32_e32 v5, s54, v163
	ds_read_b128 v[188:191], v5
	ds_read_b128 v[192:195], v5 offset:1024
	ds_read_b128 v[196:199], v5 offset:2048
	ds_read_b128 v[200:203], v5 offset:3072
	s_add_i32 m0, s43, 0xc000
	ds_read_b128 v[204:207], v166
	ds_read_b128 v[208:211], v166 offset:1024
	ds_read_b128 v[212:215], v166 offset:2048
	ds_read_b128 v[216:219], v166 offset:3072
	ds_read_b128 v[220:223], v166 offset:4096
	ds_read_b128 v[224:227], v166 offset:5120
	ds_read_b128 v[236:239], v166 offset:6144
	ds_read_b128 v[240:243], v166 offset:7168
	global_load_lds_dwordx4 v146, s[26:27]
	s_add_i32 m0, s43, 0xe000
	s_nop 0
	global_load_lds_dwordx4 v148, s[26:27]
	s_waitcnt vmcnt(8)
	s_waitcnt lgkmcnt(0)
	s_barrier
	s_setprio 1
	s_waitcnt lgkmcnt(0)
	v_mfma_f32_16x16x32_bf16 v[132:135], v[172:175], v[204:207], v[132:135]
	v_mfma_f32_16x16x32_bf16 v[128:131], v[180:183], v[204:207], v[128:131]
	v_mfma_f32_16x16x32_bf16 v[116:119], v[172:175], v[212:215], v[116:119]
	v_mfma_f32_16x16x32_bf16 v[112:115], v[180:183], v[212:215], v[112:115]
	v_mfma_f32_16x16x32_bf16 v[100:103], v[172:175], v[220:223], v[100:103]
	v_mfma_f32_16x16x32_bf16 v[96:99], v[180:183], v[220:223], v[96:99]
	v_mfma_f32_16x16x32_bf16 v[84:87], v[172:175], v[236:239], v[84:87]
	v_mfma_f32_16x16x32_bf16 v[80:83], v[180:183], v[236:239], v[80:83]
	v_mfma_f32_16x16x32_bf16 v[132:135], v[176:179], v[208:211], v[132:135]
	v_mfma_f32_16x16x32_bf16 v[128:131], v[184:187], v[208:211], v[128:131]
	v_mfma_f32_16x16x32_bf16 v[116:119], v[176:179], v[216:219], v[116:119]
	v_mfma_f32_16x16x32_bf16 v[112:115], v[184:187], v[216:219], v[112:115]
	v_mfma_f32_16x16x32_bf16 v[100:103], v[176:179], v[224:227], v[100:103]
	v_mfma_f32_16x16x32_bf16 v[96:99], v[184:187], v[224:227], v[96:99]
	v_mfma_f32_16x16x32_bf16 v[84:87], v[176:179], v[240:243], v[84:87]
	v_mfma_f32_16x16x32_bf16 v[80:83], v[184:187], v[240:243], v[80:83]
	s_setprio 0
	s_setprio 1
	v_mfma_f32_16x16x32_bf16 v[124:127], v[188:191], v[204:207], v[124:127]
	v_mfma_f32_16x16x32_bf16 v[120:123], v[196:199], v[204:207], v[120:123]
	v_mfma_f32_16x16x32_bf16 v[108:111], v[188:191], v[212:215], v[108:111]
	v_mfma_f32_16x16x32_bf16 v[104:107], v[196:199], v[212:215], v[104:107]
	v_mfma_f32_16x16x32_bf16 v[92:95], v[188:191], v[220:223], v[92:95]
	v_mfma_f32_16x16x32_bf16 v[88:91], v[196:199], v[220:223], v[88:91]
	v_mfma_f32_16x16x32_bf16 v[76:79], v[188:191], v[236:239], v[76:79]
	v_mfma_f32_16x16x32_bf16 v[72:75], v[196:199], v[236:239], v[72:75]
	v_mfma_f32_16x16x32_bf16 v[124:127], v[192:195], v[208:211], v[124:127]
	v_mfma_f32_16x16x32_bf16 v[120:123], v[200:203], v[208:211], v[120:123]
	v_mfma_f32_16x16x32_bf16 v[108:111], v[192:195], v[216:219], v[108:111]
	v_mfma_f32_16x16x32_bf16 v[104:107], v[200:203], v[216:219], v[104:107]
	v_mfma_f32_16x16x32_bf16 v[92:95], v[192:195], v[224:227], v[92:95]
	v_mfma_f32_16x16x32_bf16 v[88:91], v[200:203], v[224:227], v[88:91]
	v_mfma_f32_16x16x32_bf16 v[76:79], v[192:195], v[240:243], v[76:79]
	v_mfma_f32_16x16x32_bf16 v[72:75], v[200:203], v[240:243], v[72:75]
	s_setprio 0
	s_barrier
	s_add_i32 s71, s53, s40
	s_mov_b32 m0, s71
	ds_read_b128 v[204:207], v166 offset:16384
	ds_read_b128 v[208:211], v166 offset:17408
	ds_read_b128 v[212:215], v166 offset:18432
	ds_read_b128 v[216:219], v166 offset:19456
	ds_read_b128 v[220:223], v166 offset:20480
	ds_read_b128 v[224:227], v166 offset:21504
	ds_read_b128 v[236:239], v166 offset:22528
	ds_read_b128 v[240:243], v166 offset:23552
	global_load_lds_dwordx4 v138, s[28:29]
	s_add_i32 m0, s71, 0x2000
	s_add_u32 s72, s28, 0x100000
	s_addc_u32 s73, s29, 0
	s_add_i32 s71, s54, s40
	global_load_lds_dwordx4 v142, s[28:29]
	s_mov_b32 m0, s71
	s_nop 0
	global_load_lds_dwordx4 v138, s[72:73]
	s_add_i32 m0, s71, 0x2000
	s_nop 0
	global_load_lds_dwordx4 v142, s[72:73]
	s_mov_b32 m0, s43
	s_nop 0
	global_load_lds_dwordx4 v136, s[30:31]
	s_mov_b32 m0, s44
	s_nop 0
	global_load_lds_dwordx4 v140, s[30:31]
	s_waitcnt vmcnt(8)
	s_waitcnt lgkmcnt(0)
	s_barrier
	s_setprio 1
	s_waitcnt lgkmcnt(0)
	v_mfma_f32_16x16x32_bf16 v[68:71], v[172:175], v[204:207], v[68:71]
	v_mfma_f32_16x16x32_bf16 v[64:67], v[180:183], v[204:207], v[64:67]
	v_mfma_f32_16x16x32_bf16 v[52:55], v[172:175], v[212:215], v[52:55]
	v_mfma_f32_16x16x32_bf16 v[48:51], v[180:183], v[212:215], v[48:51]
	v_mfma_f32_16x16x32_bf16 v[36:39], v[172:175], v[220:223], v[36:39]
	v_mfma_f32_16x16x32_bf16 v[32:35], v[180:183], v[220:223], v[32:35]
	v_mfma_f32_16x16x32_bf16 v[20:23], v[172:175], v[236:239], v[20:23]
	v_mfma_f32_16x16x32_bf16 v[16:19], v[180:183], v[236:239], v[16:19]
	v_mfma_f32_16x16x32_bf16 v[68:71], v[176:179], v[208:211], v[68:71]
	v_mfma_f32_16x16x32_bf16 v[64:67], v[184:187], v[208:211], v[64:67]
	v_mfma_f32_16x16x32_bf16 v[52:55], v[176:179], v[216:219], v[52:55]
	v_mfma_f32_16x16x32_bf16 v[48:51], v[184:187], v[216:219], v[48:51]
	v_mfma_f32_16x16x32_bf16 v[36:39], v[176:179], v[224:227], v[36:39]
	v_mfma_f32_16x16x32_bf16 v[32:35], v[184:187], v[224:227], v[32:35]
	v_mfma_f32_16x16x32_bf16 v[20:23], v[176:179], v[240:243], v[20:23]
	v_mfma_f32_16x16x32_bf16 v[16:19], v[184:187], v[240:243], v[16:19]
	s_setprio 0
	s_setprio 1
	v_mfma_f32_16x16x32_bf16 v[60:63], v[188:191], v[204:207], v[60:63]
	v_mfma_f32_16x16x32_bf16 v[56:59], v[196:199], v[204:207], v[56:59]
	v_mfma_f32_16x16x32_bf16 v[44:47], v[188:191], v[212:215], v[44:47]
	v_mfma_f32_16x16x32_bf16 v[40:43], v[196:199], v[212:215], v[40:43]
	v_mfma_f32_16x16x32_bf16 v[28:31], v[188:191], v[220:223], v[28:31]
	v_mfma_f32_16x16x32_bf16 v[24:27], v[196:199], v[220:223], v[24:27]
	v_mfma_f32_16x16x32_bf16 v[12:15], v[188:191], v[236:239], v[12:15]
	v_mfma_f32_16x16x32_bf16 v[6:9], v[196:199], v[236:239], v[8:11]
	v_mfma_f32_16x16x32_bf16 v[60:63], v[192:195], v[208:211], v[60:63]
	v_mfma_f32_16x16x32_bf16 v[56:59], v[200:203], v[208:211], v[56:59]
	v_mfma_f32_16x16x32_bf16 v[44:47], v[192:195], v[216:219], v[44:47]
	v_mfma_f32_16x16x32_bf16 v[40:43], v[200:203], v[216:219], v[40:43]
	v_mfma_f32_16x16x32_bf16 v[28:31], v[192:195], v[224:227], v[28:31]
	v_mfma_f32_16x16x32_bf16 v[24:27], v[200:203], v[224:227], v[24:27]
	v_mfma_f32_16x16x32_bf16 v[12:15], v[192:195], v[240:243], v[12:15]
	v_mfma_f32_16x16x32_bf16 v[6:9], v[200:203], v[240:243], v[6:9]
	s_setprio 0
	s_barrier
	s_add_i32 s71, 0, 0x18000
	v_add_u32_e32 v5, s71, v163
	s_add_i32 s72, 0, 0x1c000
	ds_read_b128 v[172:175], v5
	ds_read_b128 v[176:179], v5 offset:1024
	ds_read_b128 v[180:183], v5 offset:2048
	ds_read_b128 v[184:187], v5 offset:3072
	v_add_u32_e32 v5, s72, v163
	ds_read_b128 v[188:191], v5
	ds_read_b128 v[192:195], v5 offset:1024
	ds_read_b128 v[196:199], v5 offset:2048
	ds_read_b128 v[200:203], v5 offset:3072
	s_add_u32 s30, s30, 0x100000
	s_addc_u32 s31, s31, 0
	s_mov_b32 m0, s45
	ds_read_b128 v[204:207], v166 offset:32768
	ds_read_b128 v[208:211], v166 offset:33792
	ds_read_b128 v[212:215], v166 offset:34816
	ds_read_b128 v[216:219], v166 offset:35840
	ds_read_b128 v[220:223], v166 offset:36864
	ds_read_b128 v[224:227], v166 offset:37888
	ds_read_b128 v[236:239], v166 offset:38912
	ds_read_b128 v[240:243], v166 offset:39936
	global_load_lds_dwordx4 v136, s[30:31]
	s_mov_b32 m0, s46
	s_nop 0
	global_load_lds_dwordx4 v140, s[30:31]
	s_waitcnt vmcnt(8)
	s_waitcnt lgkmcnt(0)
	s_barrier
	s_setprio 1
	s_waitcnt lgkmcnt(0)
	v_mfma_f32_16x16x32_bf16 v[132:135], v[172:175], v[204:207], v[132:135]
	v_mfma_f32_16x16x32_bf16 v[128:131], v[180:183], v[204:207], v[128:131]
	v_mfma_f32_16x16x32_bf16 v[116:119], v[172:175], v[212:215], v[116:119]
	v_mfma_f32_16x16x32_bf16 v[112:115], v[180:183], v[212:215], v[112:115]
	v_mfma_f32_16x16x32_bf16 v[100:103], v[172:175], v[220:223], v[100:103]
	v_mfma_f32_16x16x32_bf16 v[96:99], v[180:183], v[220:223], v[96:99]
	v_mfma_f32_16x16x32_bf16 v[84:87], v[172:175], v[236:239], v[84:87]
	v_mfma_f32_16x16x32_bf16 v[80:83], v[180:183], v[236:239], v[80:83]
	v_mfma_f32_16x16x32_bf16 v[132:135], v[176:179], v[208:211], v[132:135]
	v_mfma_f32_16x16x32_bf16 v[128:131], v[184:187], v[208:211], v[128:131]
	v_mfma_f32_16x16x32_bf16 v[116:119], v[176:179], v[216:219], v[116:119]
	v_mfma_f32_16x16x32_bf16 v[112:115], v[184:187], v[216:219], v[112:115]
	v_mfma_f32_16x16x32_bf16 v[100:103], v[176:179], v[224:227], v[100:103]
	v_mfma_f32_16x16x32_bf16 v[96:99], v[184:187], v[224:227], v[96:99]
	v_mfma_f32_16x16x32_bf16 v[84:87], v[176:179], v[240:243], v[84:87]
	v_mfma_f32_16x16x32_bf16 v[80:83], v[184:187], v[240:243], v[80:83]
	s_setprio 0
	s_setprio 1
	v_mfma_f32_16x16x32_bf16 v[124:127], v[188:191], v[204:207], v[124:127]
	v_mfma_f32_16x16x32_bf16 v[120:123], v[196:199], v[204:207], v[120:123]
	v_mfma_f32_16x16x32_bf16 v[108:111], v[188:191], v[212:215], v[108:111]
	v_mfma_f32_16x16x32_bf16 v[104:107], v[196:199], v[212:215], v[104:107]
	v_mfma_f32_16x16x32_bf16 v[92:95], v[188:191], v[220:223], v[92:95]
	v_mfma_f32_16x16x32_bf16 v[88:91], v[196:199], v[220:223], v[88:91]
	v_mfma_f32_16x16x32_bf16 v[76:79], v[188:191], v[236:239], v[76:79]
	v_mfma_f32_16x16x32_bf16 v[72:75], v[196:199], v[236:239], v[72:75]
	v_mfma_f32_16x16x32_bf16 v[124:127], v[192:195], v[208:211], v[124:127]
	v_mfma_f32_16x16x32_bf16 v[120:123], v[200:203], v[208:211], v[120:123]
	v_mfma_f32_16x16x32_bf16 v[108:111], v[192:195], v[216:219], v[108:111]
	v_mfma_f32_16x16x32_bf16 v[104:107], v[200:203], v[216:219], v[104:107]
	v_mfma_f32_16x16x32_bf16 v[92:95], v[192:195], v[224:227], v[92:95]
	v_mfma_f32_16x16x32_bf16 v[88:91], v[200:203], v[224:227], v[88:91]
	v_mfma_f32_16x16x32_bf16 v[76:79], v[192:195], v[240:243], v[76:79]
	v_mfma_f32_16x16x32_bf16 v[72:75], v[200:203], v[240:243], v[72:75]
	s_setprio 0
	s_barrier
	s_add_u32 s98, s28, s6
	s_addc_u32 s99, s29, s7
	s_add_u32 s100, s30, s6
	s_addc_u32 s101, s31, s7
	s_sub_u32 s100, s100, 0x100000
	s_subb_u32 s101, s101, 0
	s_add_i32 s30, s71, s40
	s_mov_b32 m0, s30
	ds_read_b128 v[152:155], v166 offset:49152
	ds_read_b128 v[168:171], v166 offset:50176
	ds_read_b128 v[204:207], v166 offset:51200
	ds_read_b128 v[208:211], v166 offset:52224
	ds_read_b128 v[212:215], v166 offset:53248
	ds_read_b128 v[216:219], v166 offset:54272
	ds_read_b128 v[220:223], v166 offset:55296
	ds_read_b128 v[224:227], v166 offset:56320
	global_load_lds_dwordx4 v138, s[98:99]
	s_add_i32 m0, s30, 0x2000
	s_add_u32 s28, s28, 0x100080
	s_addc_u32 s29, s29, 0
	s_add_i32 s30, s72, s40
	global_load_lds_dwordx4 v142, s[98:99]
	s_mov_b32 m0, s30
	s_nop 0
	global_load_lds_dwordx4 v138, s[28:29]
	s_add_i32 m0, s30, 0x2000
	s_nop 0
	global_load_lds_dwordx4 v142, s[28:29]
	s_mov_b32 m0, s49
	s_nop 0
	global_load_lds_dwordx4 v136, s[100:101]
	s_mov_b32 m0, s50
	s_nop 0
	global_load_lds_dwordx4 v140, s[100:101]
	s_waitcnt vmcnt(8)
	s_waitcnt lgkmcnt(0)
	s_barrier
	s_setprio 1
	s_waitcnt lgkmcnt(0)
	v_mfma_f32_16x16x32_bf16 v[68:71], v[172:175], v[152:155], v[68:71]
	v_mfma_f32_16x16x32_bf16 v[64:67], v[180:183], v[152:155], v[64:67]
	v_mfma_f32_16x16x32_bf16 v[52:55], v[172:175], v[204:207], v[52:55]
	v_mfma_f32_16x16x32_bf16 v[48:51], v[180:183], v[204:207], v[48:51]
	v_mfma_f32_16x16x32_bf16 v[36:39], v[172:175], v[212:215], v[36:39]
	v_mfma_f32_16x16x32_bf16 v[32:35], v[180:183], v[212:215], v[32:35]
	v_mfma_f32_16x16x32_bf16 v[20:23], v[172:175], v[220:223], v[20:23]
	v_mfma_f32_16x16x32_bf16 v[16:19], v[180:183], v[220:223], v[16:19]
	v_mfma_f32_16x16x32_bf16 v[68:71], v[176:179], v[168:171], v[68:71]
	v_mfma_f32_16x16x32_bf16 v[64:67], v[184:187], v[168:171], v[64:67]
	v_mfma_f32_16x16x32_bf16 v[52:55], v[176:179], v[208:211], v[52:55]
	v_mfma_f32_16x16x32_bf16 v[48:51], v[184:187], v[208:211], v[48:51]
	v_mfma_f32_16x16x32_bf16 v[36:39], v[176:179], v[216:219], v[36:39]
	v_mfma_f32_16x16x32_bf16 v[32:35], v[184:187], v[216:219], v[32:35]
	v_mfma_f32_16x16x32_bf16 v[20:23], v[176:179], v[224:227], v[20:23]
	v_mfma_f32_16x16x32_bf16 v[16:19], v[184:187], v[224:227], v[16:19]
	s_setprio 0
	s_setprio 1
	v_mfma_f32_16x16x32_bf16 v[60:63], v[188:191], v[152:155], v[60:63]
	v_mfma_f32_16x16x32_bf16 v[56:59], v[196:199], v[152:155], v[56:59]
	v_mfma_f32_16x16x32_bf16 v[44:47], v[188:191], v[204:207], v[44:47]
	v_mfma_f32_16x16x32_bf16 v[40:43], v[196:199], v[204:207], v[40:43]
	v_mfma_f32_16x16x32_bf16 v[28:31], v[188:191], v[212:215], v[28:31]
	v_mfma_f32_16x16x32_bf16 v[24:27], v[196:199], v[212:215], v[24:27]
	v_mfma_f32_16x16x32_bf16 v[10:13], v[188:191], v[220:223], v[12:15]
	v_mfma_f32_16x16x32_bf16 v[6:9], v[196:199], v[220:223], v[6:9]
	v_mfma_f32_16x16x32_bf16 v[60:63], v[192:195], v[168:171], v[60:63]
	v_mfma_f32_16x16x32_bf16 v[56:59], v[200:203], v[168:171], v[56:59]
	v_mfma_f32_16x16x32_bf16 v[44:47], v[192:195], v[208:211], v[44:47]
	v_mfma_f32_16x16x32_bf16 v[40:43], v[200:203], v[208:211], v[40:43]
	v_mfma_f32_16x16x32_bf16 v[28:31], v[192:195], v[216:219], v[28:31]
	v_mfma_f32_16x16x32_bf16 v[24:27], v[200:203], v[216:219], v[24:27]
	v_mfma_f32_16x16x32_bf16 v[12:15], v[192:195], v[224:227], v[10:13]
	v_mfma_f32_16x16x32_bf16 v[8:11], v[200:203], v[224:227], v[6:9]
	s_setprio 0
	s_barrier
	s_add_u32 s26, s26, 0x100
	s_addc_u32 s27, s27, 0
	s_add_u32 s69, s69, 0x100
	s_addc_u32 s70, s70, 0
	s_cmp_ge_i32 s8, s63
	s_cbranch_scc0 .Lp4_top
	s_branch .Lp4_epi

.LBB0_1033:
	s_add_i32 s8, s71, 2
	s_add_u32 s28, s26, 0xfff00080
	s_addc_u32 s29, s27, -1
	s_cmp_eq_u32 s68, s71
	s_cselect_b32 s31, s64, s29
	s_cselect_b32 s30, s65, s28
	s_cselect_b32 s29, s66, s70
	s_cselect_b32 s28, s67, s69
	s_cmpk_lt_i32 s3, 0x56
	s_cselect_b32 s71, s52, 0x2b00
	s_mov_b32 s72, 0xac00
	s_cselect_b32 s74, s72, 0x4000
	s_sub_i32 s71, s71, s33
	v_min3_i32 v5, s71, v160, 2
	v_sub_u32_e32 v160, v160, v5
	v_readfirstlane_b32 s71, v5
	s_max_i32 s72, s71, 0
	s_add_i32 s72, s33, s72
	s_add_i32 s75, s72, -1
	s_min_i32 s72, s33, s75
	s_mul_hi_i32 s73, s74, s72
	s_mul_i32 s72, s74, s72
	s_add_u32 s72, s34, s72
	s_addc_u32 s73, s35, s73
	s_mul_hi_i32 s76, s74, s75
	s_mul_i32 s74, s74, s75
	s_add_u32 s74, s34, s74
	global_load_dwordx4 v[152:155], v159, s[72:73] nt
	s_addc_u32 s75, s35, s76
	global_load_dwordx4 v[168:171], v159, s[74:75] nt
	s_add_i32 s33, s71, s33
	v_add_u32_e32 v5, s53, v163
	ds_read_b128 v[172:175], v5
	ds_read_b128 v[176:179], v5 offset:1024
	ds_read_b128 v[180:183], v5 offset:2048
	ds_read_b128 v[184:187], v5 offset:3072
	v_add_u32_e32 v5, s54, v163
	ds_read_b128 v[188:191], v5
	ds_read_b128 v[192:195], v5 offset:1024
	ds_read_b128 v[196:199], v5 offset:2048
	ds_read_b128 v[200:203], v5 offset:3072
	s_add_i32 m0, s43, 0xc000
	ds_read_b128 v[204:207], v166
	ds_read_b128 v[208:211], v166 offset:1024
	ds_read_b128 v[212:215], v166 offset:2048
	ds_read_b128 v[216:219], v166 offset:3072
	ds_read_b128 v[220:223], v166 offset:4096
	ds_read_b128 v[224:227], v166 offset:5120
	ds_read_b128 v[236:239], v166 offset:6144
	ds_read_b128 v[240:243], v166 offset:7168
	global_load_lds_dwordx4 v146, s[26:27]
	s_add_i32 m0, s43, 0xe000
	s_nop 0
	global_load_lds_dwordx4 v148, s[26:27]
	s_waitcnt vmcnt(10)
	s_waitcnt lgkmcnt(0)
	s_barrier
	s_setprio 1
	s_waitcnt lgkmcnt(0)
	v_mfma_f32_16x16x32_bf16 v[132:135], v[172:175], v[204:207], v[132:135]
	v_mfma_f32_16x16x32_bf16 v[128:131], v[180:183], v[204:207], v[128:131]
	v_mfma_f32_16x16x32_bf16 v[116:119], v[172:175], v[212:215], v[116:119]
	v_mfma_f32_16x16x32_bf16 v[112:115], v[180:183], v[212:215], v[112:115]
	v_mfma_f32_16x16x32_bf16 v[100:103], v[172:175], v[220:223], v[100:103]
	v_mfma_f32_16x16x32_bf16 v[96:99], v[180:183], v[220:223], v[96:99]
	v_mfma_f32_16x16x32_bf16 v[84:87], v[172:175], v[236:239], v[84:87]
	v_mfma_f32_16x16x32_bf16 v[80:83], v[180:183], v[236:239], v[80:83]
	v_mfma_f32_16x16x32_bf16 v[132:135], v[176:179], v[208:211], v[132:135]
	v_mfma_f32_16x16x32_bf16 v[128:131], v[184:187], v[208:211], v[128:131]
	v_mfma_f32_16x16x32_bf16 v[116:119], v[176:179], v[216:219], v[116:119]
	v_mfma_f32_16x16x32_bf16 v[112:115], v[184:187], v[216:219], v[112:115]
	v_mfma_f32_16x16x32_bf16 v[100:103], v[176:179], v[224:227], v[100:103]
	v_mfma_f32_16x16x32_bf16 v[96:99], v[184:187], v[224:227], v[96:99]
	v_mfma_f32_16x16x32_bf16 v[84:87], v[176:179], v[240:243], v[84:87]
	v_mfma_f32_16x16x32_bf16 v[80:83], v[184:187], v[240:243], v[80:83]
	s_setprio 0
	s_setprio 1
	v_mfma_f32_16x16x32_bf16 v[124:127], v[188:191], v[204:207], v[124:127]
	v_mfma_f32_16x16x32_bf16 v[120:123], v[196:199], v[204:207], v[120:123]
	v_mfma_f32_16x16x32_bf16 v[108:111], v[188:191], v[212:215], v[108:111]
	v_mfma_f32_16x16x32_bf16 v[104:107], v[196:199], v[212:215], v[104:107]
	v_mfma_f32_16x16x32_bf16 v[92:95], v[188:191], v[220:223], v[92:95]
	v_mfma_f32_16x16x32_bf16 v[88:91], v[196:199], v[220:223], v[88:91]
	v_mfma_f32_16x16x32_bf16 v[76:79], v[188:191], v[236:239], v[76:79]
	v_mfma_f32_16x16x32_bf16 v[72:75], v[196:199], v[236:239], v[72:75]
	v_mfma_f32_16x16x32_bf16 v[124:127], v[192:195], v[208:211], v[124:127]
	v_mfma_f32_16x16x32_bf16 v[120:123], v[200:203], v[208:211], v[120:123]
	v_mfma_f32_16x16x32_bf16 v[108:111], v[192:195], v[216:219], v[108:111]
	v_mfma_f32_16x16x32_bf16 v[104:107], v[200:203], v[216:219], v[104:107]
	v_mfma_f32_16x16x32_bf16 v[92:95], v[192:195], v[224:227], v[92:95]
	v_mfma_f32_16x16x32_bf16 v[88:91], v[200:203], v[224:227], v[88:91]
	v_mfma_f32_16x16x32_bf16 v[76:79], v[192:195], v[240:243], v[76:79]
	v_mfma_f32_16x16x32_bf16 v[72:75], v[200:203], v[240:243], v[72:75]
	s_setprio 0
	s_barrier
	s_add_i32 s71, s53, s40
	s_mov_b32 m0, s71
	ds_read_b128 v[204:207], v166 offset:16384
	ds_read_b128 v[208:211], v166 offset:17408
	ds_read_b128 v[212:215], v166 offset:18432
	ds_read_b128 v[216:219], v166 offset:19456
	ds_read_b128 v[220:223], v166 offset:20480
	ds_read_b128 v[224:227], v166 offset:21504
	ds_read_b128 v[236:239], v166 offset:22528
	ds_read_b128 v[240:243], v166 offset:23552
	global_load_lds_dwordx4 v138, s[28:29]
	s_add_i32 m0, s71, 0x2000
	s_add_u32 s72, s28, 0x100000
	s_addc_u32 s73, s29, 0
	s_add_i32 s71, s54, s40
	global_load_lds_dwordx4 v142, s[28:29]
	s_mov_b32 m0, s71
	s_nop 0
	global_load_lds_dwordx4 v138, s[72:73]
	s_add_i32 m0, s71, 0x2000
	s_nop 0
	global_load_lds_dwordx4 v142, s[72:73]
	s_mov_b32 m0, s43
	s_nop 0
	global_load_lds_dwordx4 v136, s[30:31]
	s_mov_b32 m0, s44
	s_nop 0
	global_load_lds_dwordx4 v140, s[30:31]
	s_waitcnt vmcnt(10)
	s_waitcnt lgkmcnt(0)
	s_barrier
	s_setprio 1
	s_waitcnt lgkmcnt(0)
	v_mfma_f32_16x16x32_bf16 v[68:71], v[172:175], v[204:207], v[68:71]
	v_mfma_f32_16x16x32_bf16 v[64:67], v[180:183], v[204:207], v[64:67]
	v_mfma_f32_16x16x32_bf16 v[52:55], v[172:175], v[212:215], v[52:55]
	v_mfma_f32_16x16x32_bf16 v[48:51], v[180:183], v[212:215], v[48:51]
	v_mfma_f32_16x16x32_bf16 v[36:39], v[172:175], v[220:223], v[36:39]
	v_mfma_f32_16x16x32_bf16 v[32:35], v[180:183], v[220:223], v[32:35]
	v_mfma_f32_16x16x32_bf16 v[20:23], v[172:175], v[236:239], v[20:23]
	v_mfma_f32_16x16x32_bf16 v[16:19], v[180:183], v[236:239], v[16:19]
	v_mfma_f32_16x16x32_bf16 v[68:71], v[176:179], v[208:211], v[68:71]
	v_mfma_f32_16x16x32_bf16 v[64:67], v[184:187], v[208:211], v[64:67]
	v_mfma_f32_16x16x32_bf16 v[52:55], v[176:179], v[216:219], v[52:55]
	v_mfma_f32_16x16x32_bf16 v[48:51], v[184:187], v[216:219], v[48:51]
	v_mfma_f32_16x16x32_bf16 v[36:39], v[176:179], v[224:227], v[36:39]
	v_mfma_f32_16x16x32_bf16 v[32:35], v[184:187], v[224:227], v[32:35]
	v_mfma_f32_16x16x32_bf16 v[20:23], v[176:179], v[240:243], v[20:23]
	v_mfma_f32_16x16x32_bf16 v[16:19], v[184:187], v[240:243], v[16:19]
	s_setprio 0
	s_setprio 1
	v_mfma_f32_16x16x32_bf16 v[60:63], v[188:191], v[204:207], v[60:63]
	v_mfma_f32_16x16x32_bf16 v[56:59], v[196:199], v[204:207], v[56:59]
	v_mfma_f32_16x16x32_bf16 v[44:47], v[188:191], v[212:215], v[44:47]
	v_mfma_f32_16x16x32_bf16 v[40:43], v[196:199], v[212:215], v[40:43]
	v_mfma_f32_16x16x32_bf16 v[28:31], v[188:191], v[220:223], v[28:31]
	v_mfma_f32_16x16x32_bf16 v[24:27], v[196:199], v[220:223], v[24:27]
	v_mfma_f32_16x16x32_bf16 v[12:15], v[188:191], v[236:239], v[12:15]
	v_mfma_f32_16x16x32_bf16 v[6:9], v[196:199], v[236:239], v[8:11]
	v_mfma_f32_16x16x32_bf16 v[60:63], v[192:195], v[208:211], v[60:63]
	v_mfma_f32_16x16x32_bf16 v[56:59], v[200:203], v[208:211], v[56:59]
	v_mfma_f32_16x16x32_bf16 v[44:47], v[192:195], v[216:219], v[44:47]
	v_mfma_f32_16x16x32_bf16 v[40:43], v[200:203], v[216:219], v[40:43]
	v_mfma_f32_16x16x32_bf16 v[28:31], v[192:195], v[224:227], v[28:31]
	v_mfma_f32_16x16x32_bf16 v[24:27], v[200:203], v[224:227], v[24:27]
	v_mfma_f32_16x16x32_bf16 v[12:15], v[192:195], v[240:243], v[12:15]
	v_mfma_f32_16x16x32_bf16 v[6:9], v[200:203], v[240:243], v[6:9]
	s_setprio 0
	s_barrier
	s_add_i32 s71, 0, 0x18000
	v_add_u32_e32 v5, s71, v163
	s_add_i32 s72, 0, 0x1c000
	ds_read_b128 v[172:175], v5
	ds_read_b128 v[176:179], v5 offset:1024
	ds_read_b128 v[180:183], v5 offset:2048
	ds_read_b128 v[184:187], v5 offset:3072
	v_add_u32_e32 v5, s72, v163
	ds_read_b128 v[188:191], v5
	ds_read_b128 v[192:195], v5 offset:1024
	ds_read_b128 v[196:199], v5 offset:2048
	ds_read_b128 v[200:203], v5 offset:3072
	s_add_u32 s30, s30, 0x100000
	s_addc_u32 s31, s31, 0
	s_mov_b32 m0, s45
	ds_read_b128 v[204:207], v166 offset:32768
	ds_read_b128 v[208:211], v166 offset:33792
	ds_read_b128 v[212:215], v166 offset:34816
	ds_read_b128 v[216:219], v166 offset:35840
	ds_read_b128 v[220:223], v166 offset:36864
	ds_read_b128 v[224:227], v166 offset:37888
	ds_read_b128 v[236:239], v166 offset:38912
	ds_read_b128 v[240:243], v166 offset:39936
	global_load_lds_dwordx4 v136, s[30:31]
	s_mov_b32 m0, s46
	s_nop 0
	global_load_lds_dwordx4 v140, s[30:31]
	s_waitcnt vmcnt(8)
	s_waitcnt lgkmcnt(0)
	s_barrier
	s_setprio 1
	s_waitcnt lgkmcnt(0)
	v_mfma_f32_16x16x32_bf16 v[132:135], v[172:175], v[204:207], v[132:135]
	v_mfma_f32_16x16x32_bf16 v[128:131], v[180:183], v[204:207], v[128:131]
	v_mfma_f32_16x16x32_bf16 v[116:119], v[172:175], v[212:215], v[116:119]
	v_mfma_f32_16x16x32_bf16 v[112:115], v[180:183], v[212:215], v[112:115]
	v_mfma_f32_16x16x32_bf16 v[100:103], v[172:175], v[220:223], v[100:103]
	v_max3_f32 v0, v0, |v152|, |v168|
	v_mfma_f32_16x16x32_bf16 v[96:99], v[180:183], v[220:223], v[96:99]
	v_max3_f32 v1, v1, |v153|, |v169|
	v_mfma_f32_16x16x32_bf16 v[84:87], v[172:175], v[236:239], v[84:87]
	v_max3_f32 v2, v2, |v154|, |v170|
	v_mfma_f32_16x16x32_bf16 v[80:83], v[180:183], v[236:239], v[80:83]
	v_max3_f32 v3, v3, |v155|, |v171|
	v_mfma_f32_16x16x32_bf16 v[132:135], v[176:179], v[208:211], v[132:135]
	v_mfma_f32_16x16x32_bf16 v[128:131], v[184:187], v[208:211], v[128:131]
	v_mfma_f32_16x16x32_bf16 v[116:119], v[176:179], v[216:219], v[116:119]
	v_mfma_f32_16x16x32_bf16 v[112:115], v[184:187], v[216:219], v[112:115]
	v_mfma_f32_16x16x32_bf16 v[100:103], v[176:179], v[224:227], v[100:103]
	v_mfma_f32_16x16x32_bf16 v[96:99], v[184:187], v[224:227], v[96:99]
	v_mfma_f32_16x16x32_bf16 v[84:87], v[176:179], v[240:243], v[84:87]
	v_mfma_f32_16x16x32_bf16 v[80:83], v[184:187], v[240:243], v[80:83]
	s_setprio 0
	s_setprio 1
	v_mfma_f32_16x16x32_bf16 v[124:127], v[188:191], v[204:207], v[124:127]
	v_mfma_f32_16x16x32_bf16 v[120:123], v[196:199], v[204:207], v[120:123]
	v_mfma_f32_16x16x32_bf16 v[108:111], v[188:191], v[212:215], v[108:111]
	v_mfma_f32_16x16x32_bf16 v[104:107], v[196:199], v[212:215], v[104:107]
	v_mfma_f32_16x16x32_bf16 v[92:95], v[188:191], v[220:223], v[92:95]
	v_mfma_f32_16x16x32_bf16 v[88:91], v[196:199], v[220:223], v[88:91]
	v_mfma_f32_16x16x32_bf16 v[76:79], v[188:191], v[236:239], v[76:79]
	v_mfma_f32_16x16x32_bf16 v[72:75], v[196:199], v[236:239], v[72:75]
	v_mfma_f32_16x16x32_bf16 v[124:127], v[192:195], v[208:211], v[124:127]
	v_mfma_f32_16x16x32_bf16 v[120:123], v[200:203], v[208:211], v[120:123]
	v_mfma_f32_16x16x32_bf16 v[108:111], v[192:195], v[216:219], v[108:111]
	v_mfma_f32_16x16x32_bf16 v[104:107], v[200:203], v[216:219], v[104:107]
	v_mfma_f32_16x16x32_bf16 v[92:95], v[192:195], v[224:227], v[92:95]
	v_mfma_f32_16x16x32_bf16 v[88:91], v[200:203], v[224:227], v[88:91]
	v_mfma_f32_16x16x32_bf16 v[76:79], v[192:195], v[240:243], v[76:79]
	v_mfma_f32_16x16x32_bf16 v[72:75], v[200:203], v[240:243], v[72:75]
	s_setprio 0
	s_barrier
	s_add_u32 s98, s28, s6
	s_addc_u32 s99, s29, s7
	s_add_u32 s100, s30, s6
	s_addc_u32 s101, s31, s7
	s_sub_u32 s100, s100, 0x100000
	s_subb_u32 s101, s101, 0
	s_add_i32 s30, s71, s40
	s_mov_b32 m0, s30
	ds_read_b128 v[152:155], v166 offset:49152
	ds_read_b128 v[168:171], v166 offset:50176
	ds_read_b128 v[204:207], v166 offset:51200
	ds_read_b128 v[208:211], v166 offset:52224
	ds_read_b128 v[212:215], v166 offset:53248
	ds_read_b128 v[216:219], v166 offset:54272
	ds_read_b128 v[220:223], v166 offset:55296
	ds_read_b128 v[224:227], v166 offset:56320
	global_load_lds_dwordx4 v138, s[98:99]
	s_add_i32 m0, s30, 0x2000
	s_add_u32 s28, s28, 0x100080
	s_addc_u32 s29, s29, 0
	s_add_i32 s30, s72, s40
	global_load_lds_dwordx4 v142, s[98:99]
	s_mov_b32 m0, s30
	s_nop 0
	global_load_lds_dwordx4 v138, s[28:29]
	s_add_i32 m0, s30, 0x2000
	s_nop 0
	global_load_lds_dwordx4 v142, s[28:29]
	s_mov_b32 m0, s49
	s_nop 0
	global_load_lds_dwordx4 v136, s[100:101]
	s_mov_b32 m0, s50
	s_nop 0
	global_load_lds_dwordx4 v140, s[100:101]
	s_waitcnt vmcnt(8)
	s_waitcnt lgkmcnt(0)
	s_barrier
	s_setprio 1
	s_waitcnt lgkmcnt(0)
	v_mfma_f32_16x16x32_bf16 v[68:71], v[172:175], v[152:155], v[68:71]
	v_mfma_f32_16x16x32_bf16 v[64:67], v[180:183], v[152:155], v[64:67]
	v_mfma_f32_16x16x32_bf16 v[52:55], v[172:175], v[204:207], v[52:55]
	v_mfma_f32_16x16x32_bf16 v[48:51], v[180:183], v[204:207], v[48:51]
	v_mfma_f32_16x16x32_bf16 v[36:39], v[172:175], v[212:215], v[36:39]
	v_mfma_f32_16x16x32_bf16 v[32:35], v[180:183], v[212:215], v[32:35]
	v_mfma_f32_16x16x32_bf16 v[20:23], v[172:175], v[220:223], v[20:23]
	v_mfma_f32_16x16x32_bf16 v[16:19], v[180:183], v[220:223], v[16:19]
	v_mfma_f32_16x16x32_bf16 v[68:71], v[176:179], v[168:171], v[68:71]
	v_mfma_f32_16x16x32_bf16 v[64:67], v[184:187], v[168:171], v[64:67]
	v_mfma_f32_16x16x32_bf16 v[52:55], v[176:179], v[208:211], v[52:55]
	v_mfma_f32_16x16x32_bf16 v[48:51], v[184:187], v[208:211], v[48:51]
	v_mfma_f32_16x16x32_bf16 v[36:39], v[176:179], v[216:219], v[36:39]
	v_mfma_f32_16x16x32_bf16 v[32:35], v[184:187], v[216:219], v[32:35]
	v_mfma_f32_16x16x32_bf16 v[20:23], v[176:179], v[224:227], v[20:23]
	v_mfma_f32_16x16x32_bf16 v[16:19], v[184:187], v[224:227], v[16:19]
	s_setprio 0
	s_setprio 1
	v_mfma_f32_16x16x32_bf16 v[60:63], v[188:191], v[152:155], v[60:63]
	v_mfma_f32_16x16x32_bf16 v[56:59], v[196:199], v[152:155], v[56:59]
	v_mfma_f32_16x16x32_bf16 v[44:47], v[188:191], v[204:207], v[44:47]
	v_mfma_f32_16x16x32_bf16 v[40:43], v[196:199], v[204:207], v[40:43]
	v_mfma_f32_16x16x32_bf16 v[28:31], v[188:191], v[212:215], v[28:31]
	v_mfma_f32_16x16x32_bf16 v[24:27], v[196:199], v[212:215], v[24:27]
	v_mfma_f32_16x16x32_bf16 v[10:13], v[188:191], v[220:223], v[12:15]
	v_mfma_f32_16x16x32_bf16 v[6:9], v[196:199], v[220:223], v[6:9]
	v_mfma_f32_16x16x32_bf16 v[60:63], v[192:195], v[168:171], v[60:63]
	v_mfma_f32_16x16x32_bf16 v[56:59], v[200:203], v[168:171], v[56:59]
	v_mfma_f32_16x16x32_bf16 v[44:47], v[192:195], v[208:211], v[44:47]
	v_mfma_f32_16x16x32_bf16 v[40:43], v[200:203], v[208:211], v[40:43]
	v_mfma_f32_16x16x32_bf16 v[28:31], v[192:195], v[216:219], v[28:31]
	v_mfma_f32_16x16x32_bf16 v[24:27], v[200:203], v[216:219], v[24:27]
	v_mfma_f32_16x16x32_bf16 v[12:15], v[192:195], v[224:227], v[10:13]
	v_mfma_f32_16x16x32_bf16 v[8:11], v[200:203], v[224:227], v[6:9]
	s_setprio 0
	s_barrier
	s_add_u32 s26, s26, 0x100
	s_addc_u32 s27, s27, 0
	s_add_u32 s69, s69, 0x100
	s_addc_u32 s70, s70, 0
	s_cmp_ge_i32 s8, s63
	s_cbranch_scc0 .LBB0_1018
